# speedup vs baseline: 1.0264x; 1.0264x over previous
; __device__ __forceinline__ bf16x8 gld16(const void* p) { bf16x8 v; asm volatile("global_load_dwordx4 %0, %1, off" : "=v"(v) : "v"(p) : "memory"); return v; }
;   __device__ __forceinline__ bfu* pb() const { return (bfu*)(b + L::o_pb); }
;   __device__ __forceinline__ float* gl() const { return (float*)(b + L::o_gl); }
;   __device__ __forceinline__ bfu* rb() const { return (bfu*)(b + L::o_rb); }
; template <bool SWAP>
; __device__ __forceinline__ void gemm_big(const bfu* __restrict__ A, int lda, const bfu* __restrict__ B, int ldb, int K,
;                                          f32x4 (&acc)[8][4], bfu* sm, const bfu* An = nullptr, const bfu* Bn = nullptr) {
;     ...
;   const int lrow = tid >> 2, lch = (tid & 3) * 8;
;   const bfu* Ap = A + (size_t)lrow * lda + lch;
;   const bfu* Bp = B + (size_t)lrow * ldb + lch;
;   int brow = lrow;
;   if (SWAP) brow = ((lrow & 12) << 2) | ((lrow >> 2) & 12) | (lrow & 3);
;   const int nk = K >> 5;
;   const bool chain = (An != nullptr);
;   const bfu* Apn = chain ? (An + (size_t)lrow * lda + lch) : Ap;
;   const bfu* Bpn = chain ? (Bn + (size_t)lrow * ldb + lch) : Bp;
;   auto gl = [&](bf16x8 (&ra)[4], bf16x8 (&rb)[2], int kt) {
;     const bool nx = (kt >= nk);
;     const bfu* pa = nx ? (chain ? Apn + (kt - nk) * 32 : Ap + (nk - 1) * 32) : Ap + kt * 32;
;     const bfu* pb = nx ? (chain ? Bpn + (kt - nk) * 32 : Bp + (nk - 1) * 32) : Bp + kt * 32;
; #pragma unroll
;     for (int q = 0; q < 4; ++q) ra[q] = gld16(pa + (size_t)(64 * q) * lda);
; #pragma unroll
;     for (int q = 0; q < 2; ++q) rb[q] = gld16(pb + (size_t)(64 * q) * ldb);
;   };
;   auto wt = [&](bf16x8 (&ra)[4], bf16x8 (&rb)[2]) {
;     asm volatile("s_waitcnt vmcnt(6)" : "+v"(ra[0]), "+v"(ra[1]), "+v"(ra[2]), "+v"(ra[3]), "+v"(rb[0]), "+v"(rb[1]) : : "memory");
;   };
;   auto st = [&](const bf16x8 (&ra)[4], const bf16x8 (&rb)[2], int buf) {
; #pragma unroll
;     for (int q = 0; q < 4; ++q) *(bf16x8*)(As + (buf * 256 + lrow + 64 * q) * 40 + lch) = ra[q];
; #pragma unroll
;     for (int q = 0; q < 2; ++q) *(bf16x8*)(Bs + (buf * 128 + brow + 64 * q) * 40 + lch) = rb[q];
;     ...
;   gl(ra0, rb0, 0);
;   gl(ra1, rb1, 1);
;   __syncthreads();
;   wt(ra0, rb0);
;   st(ra0, rb0, 0);
;   __syncthreads();
.LBB0_109:
	v_mov_b32_e32 v27, v174
	s_mov_b64 s[0:1], 0x20040
	v_ashrrev_i32_e32 v24, 2, v27
	v_ashrrev_i32_e32 v25, 31, v24
	v_lshlrev_b64 v[0:1], 11, v[24:25]
	v_lshlrev_b32_e32 v4, 4, v27
	v_lshl_add_u64 v[2:3], s[18:19], 0, v[0:1]
	v_and_b32_e32 v152, 48, v4
	v_lshl_add_u64 v[164:165], v[2:3], 0, v[152:153]
	v_lshl_add_u64 v[2:3], s[20:21], 0, v[0:1]
	v_lshl_add_u64 v[166:167], v[2:3], 0, v[152:153]
	v_lshrrev_b32_e32 v2, 2, v24
	v_and_b32_e32 v26, 48, v27
	v_and_b32_e32 v2, 12, v2
	v_and_b32_e32 v3, 3, v24
	v_or3_b32 v25, v26, v3, v2
	v_lshl_add_u64 v[2:3], s[22:23], 0, v[0:1]
	v_lshl_add_u64 v[0:1], s[24:25], 0, v[0:1]
	v_lshl_add_u64 v[28:29], v[2:3], 0, v[152:153]
	v_lshl_add_u64 v[30:31], v[0:1], 0, v[152:153]
	global_load_dwordx4 v[0:3], v[164:165], off
	v_lshl_add_u64 v[4:5], v[164:165], 0, s[8:9]
	global_load_dwordx4 v[4:7], v[4:5], off
	v_lshl_add_u64 v[8:9], v[164:165], 0, s[4:5]
	global_load_dwordx4 v[8:11], v[8:9], off
	v_lshl_add_u64 v[12:13], v[164:165], 0, s[90:91]
	global_load_dwordx4 v[12:15], v[12:13], off
	global_load_dwordx4 v[16:19], v[166:167], off
	v_lshl_add_u64 v[20:21], v[166:167], 0, s[8:9]
	global_load_dwordx4 v[20:23], v[20:21], off
	v_lshl_add_u64 v[32:33], v[164:165], 0, 64
	global_load_dwordx4 v[128:131], v[32:33], off
	v_lshl_add_u64 v[32:33], v[164:165], 0, s[0:1]
	global_load_dwordx4 v[132:135], v[32:33], off
	s_mov_b64 s[28:29], 0x40040
	v_lshl_add_u64 v[32:33], v[164:165], 0, s[28:29]
	global_load_dwordx4 v[136:139], v[32:33], off
	s_mov_b64 s[28:29], 0x60040
	v_lshl_add_u64 v[32:33], v[164:165], 0, s[28:29]
	global_load_dwordx4 v[140:143], v[32:33], off
	v_lshl_add_u64 v[34:35], v[166:167], 0, 64
	global_load_dwordx4 v[144:147], v[34:35], off
	v_lshl_add_u64 v[32:33], v[166:167], 0, s[0:1]
	global_load_dwordx4 v[148:151], v[32:33], off
	s_barrier
	s_waitcnt vmcnt(6)
	s_movk_i32 s2, 0x50
	v_add_u32_e32 v36, 4, v24
	v_and_b32_e32 v36, 8, v36
	v_lshlrev_b32_e32 v36, 1, v36
	v_xor_b32_e32 v36, v152, v36
	v_mad_u32_u24 v168, v24, s2, v36
	ds_write_b128 v168, v[0:3]
	ds_write_b128 v168, v[4:7] offset:5120
	ds_write_b128 v168, v[8:11] offset:10240
	ds_write_b128 v168, v[12:15] offset:15360
	v_and_b32_e32 v0, 0xfffff8f, v27
	v_and_b32_e32 v1, 0x4f, v27
	v_add_u32_e32 v37, 4, v25
	v_and_b32_e32 v37, 8, v37
	v_lshlrev_b32_e32 v37, 1, v37
	v_xor_b32_e32 v37, v152, v37
	v_mad_u32_u24 v169, v25, s2, v37
	v_mul_u32_u24_e32 v1, 40, v1
	v_add_u32_e32 v38, 4, v27
	v_and_b32_e32 v38, 8, v38
	v_lshlrev_b32_e32 v38, 1, v38
	v_xor_b32_e32 v38, v26, v38
	v_mad_u32_u24 v172, v0, s2, v38
	v_mov_b32_e32 v0, 0
	ds_write_b128 v169, v[16:19] offset:40960
	ds_write_b128 v169, v[20:23] offset:46080
	v_cndmask_b32_e64 v157, v29, v165, s[10:11]
	v_cndmask_b32_e64 v152, v28, v164, s[10:11]
	v_cndmask_b32_e64 v159, v31, v167, s[10:11]
	v_cndmask_b32_e64 v170, v30, v166, s[10:11]
	v_lshl_add_u32 v199, v1, 1, v38
	s_mov_b32 s17, 0
	s_movk_i32 s15, 0xfc40
	v_mov_b32_e32 v1, v0
	v_mov_b32_e32 v2, v0
	v_mov_b32_e32 v3, v0
	v_mov_b32_e32 v4, v0
	v_mov_b32_e32 v5, v0
	v_mov_b32_e32 v6, v0
	v_mov_b32_e32 v7, v0
	v_mov_b32_e32 v8, v0
	v_mov_b32_e32 v9, v0
	v_mov_b32_e32 v10, v0
	v_mov_b32_e32 v11, v0
	v_mov_b32_e32 v12, v0
	v_mov_b32_e32 v13, v0
	v_mov_b32_e32 v14, v0
	v_mov_b32_e32 v15, v0
	v_mov_b32_e32 v16, v0
	v_mov_b32_e32 v17, v0
	v_mov_b32_e32 v18, v0
	v_mov_b32_e32 v19, v0
	v_mov_b32_e32 v20, v0
	v_mov_b32_e32 v21, v0
	v_mov_b32_e32 v22, v0
	v_mov_b32_e32 v23, v0
	v_mov_b32_e32 v24, v0
	v_mov_b32_e32 v25, v0
	v_mov_b32_e32 v26, v0
	v_mov_b32_e32 v27, v0
	v_mov_b32_e32 v28, v0
	v_mov_b32_e32 v29, v0
	v_mov_b32_e32 v30, v0
	v_mov_b32_e32 v31, v0
	v_mov_b32_e32 v32, v0
	v_mov_b32_e32 v33, v0
	v_mov_b32_e32 v34, v0
	v_mov_b32_e32 v35, v0
	v_mov_b32_e32 v36, v0
	v_mov_b32_e32 v37, v0
	v_mov_b32_e32 v38, v0
	v_mov_b32_e32 v39, v0
	v_mov_b32_e32 v40, v0
	v_mov_b32_e32 v41, v0
	v_mov_b32_e32 v42, v0
	v_mov_b32_e32 v43, v0
	v_mov_b32_e32 v44, v0
	v_mov_b32_e32 v45, v0
	v_mov_b32_e32 v46, v0
	v_mov_b32_e32 v47, v0
	v_mov_b32_e32 v48, v0
	v_mov_b32_e32 v49, v0
	v_mov_b32_e32 v50, v0
	v_mov_b32_e32 v51, v0
	v_mov_b32_e32 v52, v0
	v_mov_b32_e32 v53, v0
	v_mov_b32_e32 v54, v0
	v_mov_b32_e32 v55, v0
	v_mov_b32_e32 v56, v0
	v_mov_b32_e32 v57, v0
	v_mov_b32_e32 v58, v0
	v_mov_b32_e32 v59, v0
	v_mov_b32_e32 v60, v0
	v_mov_b32_e32 v61, v0
	v_mov_b32_e32 v62, v0
	v_mov_b32_e32 v63, v0
	v_mov_b32_e32 v64, v0
	v_mov_b32_e32 v65, v0
	v_mov_b32_e32 v66, v0
	v_mov_b32_e32 v67, v0
	v_mov_b32_e32 v68, v0
	v_mov_b32_e32 v69, v0
	v_mov_b32_e32 v70, v0
	v_mov_b32_e32 v71, v0
	v_mov_b32_e32 v72, v0
	v_mov_b32_e32 v73, v0
	v_mov_b32_e32 v74, v0
	v_mov_b32_e32 v75, v0
	v_mov_b32_e32 v76, v0
	v_mov_b32_e32 v77, v0
	v_mov_b32_e32 v78, v0
	v_mov_b32_e32 v79, v0
	v_mov_b32_e32 v80, v0
	v_mov_b32_e32 v81, v0
	v_mov_b32_e32 v82, v0
	v_mov_b32_e32 v83, v0
	v_mov_b32_e32 v84, v0
	v_mov_b32_e32 v85, v0
	v_mov_b32_e32 v86, v0
	v_mov_b32_e32 v87, v0
	v_mov_b32_e32 v88, v0
	v_mov_b32_e32 v89, v0
	v_mov_b32_e32 v90, v0
	v_mov_b32_e32 v91, v0
	v_mov_b32_e32 v92, v0
	v_mov_b32_e32 v93, v0
	v_mov_b32_e32 v94, v0
	v_mov_b32_e32 v95, v0
	v_mov_b32_e32 v96, v0
	v_mov_b32_e32 v97, v0
	v_mov_b32_e32 v98, v0
	v_mov_b32_e32 v99, v0
	v_mov_b32_e32 v100, v0
	v_mov_b32_e32 v101, v0
	v_mov_b32_e32 v102, v0
	v_mov_b32_e32 v103, v0
	v_mov_b32_e32 v104, v0
	v_mov_b32_e32 v105, v0
	v_mov_b32_e32 v106, v0
	v_mov_b32_e32 v107, v0
	v_mov_b32_e32 v108, v0
	v_mov_b32_e32 v109, v0
	v_mov_b32_e32 v110, v0
	v_mov_b32_e32 v111, v0
	v_mov_b32_e32 v112, v0
	v_mov_b32_e32 v113, v0
	v_mov_b32_e32 v114, v0
	v_mov_b32_e32 v115, v0
	v_mov_b32_e32 v116, v0
	v_mov_b32_e32 v117, v0
	v_mov_b32_e32 v118, v0
	v_mov_b32_e32 v119, v0
	v_mov_b32_e32 v120, v0
	v_mov_b32_e32 v121, v0
	v_mov_b32_e32 v122, v0
	v_mov_b32_e32 v123, v0
	v_mov_b32_e32 v124, v0
	v_mov_b32_e32 v125, v0
	v_mov_b32_e32 v126, v0
	v_mov_b32_e32 v127, v0
	s_waitcnt lgkmcnt(0)
	s_barrier

; __device__ __forceinline__ bf16x8 gld16(const void* p) { bf16x8 v; asm volatile("global_load_dwordx4 %0, %1, off" : "=v"(v) : "v"(p) : "memory"); return v; }
;   __device__ __forceinline__ bfu* pb() const { return (bfu*)(b + L::o_pb); }
;   __device__ __forceinline__ float* gl() const { return (float*)(b + L::o_gl); }
;   __device__ __forceinline__ bfu* rb() const { return (bfu*)(b + L::o_rb); }
; template <bool SWAP>
; __device__ __forceinline__ void gemm_big(const bfu* __restrict__ A, int lda, const bfu* __restrict__ B, int ldb, int K,
;                                          f32x4 (&acc)[8][4], bfu* sm, const bfu* An = nullptr, const bfu* Bn = nullptr) {
;     ...
;   const int lrow = tid >> 2, lch = (tid & 3) * 8;
;   const bfu* Ap = A + (size_t)lrow * lda + lch;
;   const bfu* Bp = B + (size_t)lrow * ldb + lch;
;   int brow = lrow;
;   if (SWAP) brow = ((lrow & 12) << 2) | ((lrow >> 2) & 12) | (lrow & 3);
;   const int nk = K >> 5;
;   const bool chain = (An != nullptr);
;   const bfu* Apn = chain ? (An + (size_t)lrow * lda + lch) : Ap;
;   const bfu* Bpn = chain ? (Bn + (size_t)lrow * ldb + lch) : Bp;
;   auto gl = [&](bf16x8 (&ra)[4], bf16x8 (&rb)[2], int kt) {
;     const bool nx = (kt >= nk);
;     const bfu* pa = nx ? (chain ? Apn + (kt - nk) * 32 : Ap + (nk - 1) * 32) : Ap + kt * 32;
;     const bfu* pb = nx ? (chain ? Bpn + (kt - nk) * 32 : Bp + (nk - 1) * 32) : Bp + kt * 32;
; #pragma unroll
;     for (int q = 0; q < 4; ++q) ra[q] = gld16(pa + (size_t)(64 * q) * lda);
; #pragma unroll
;     for (int q = 0; q < 2; ++q) rb[q] = gld16(pb + (size_t)(64 * q) * ldb);
;   };
;   auto wt = [&](bf16x8 (&ra)[4], bf16x8 (&rb)[2]) {
;     asm volatile("s_waitcnt vmcnt(6)" : "+v"(ra[0]), "+v"(ra[1]), "+v"(ra[2]), "+v"(ra[3]), "+v"(rb[0]), "+v"(rb[1]) : : "memory");
;   };
;   auto st = [&](const bf16x8 (&ra)[4], const bf16x8 (&rb)[2], int buf) {
; #pragma unroll
;     for (int q = 0; q < 4; ++q) *(bf16x8*)(As + (buf * 256 + lrow + 64 * q) * 40 + lch) = ra[q];
; #pragma unroll
;     for (int q = 0; q < 2; ++q) *(bf16x8*)(Bs + (buf * 128 + brow + 64 * q) * 40 + lch) = rb[q];
;     ...
;   gl(ra0, rb0, 0);
;   gl(ra1, rb1, 1);
;   __syncthreads();
;   wt(ra0, rb0);
;   st(ra0, rb0, 0);
;   __syncthreads();
.LBB0_131:
	v_mov_b32_e32 v34, v174
	s_mov_b64 s[0:1], 0x20040
	v_ashrrev_i32_e32 v24, 2, v34
	v_ashrrev_i32_e32 v25, 31, v24
	v_lshlrev_b64 v[0:1], 11, v[24:25]
	v_lshlrev_b32_e32 v4, 4, v34
	v_lshl_add_u64 v[2:3], s[18:19], 0, v[0:1]
	v_and_b32_e32 v152, 48, v4
	v_lshl_add_u64 v[164:165], v[2:3], 0, v[152:153]
	v_lshl_add_u64 v[2:3], s[20:21], 0, v[0:1]
	v_lshl_add_u64 v[166:167], v[2:3], 0, v[152:153]
	v_lshl_add_u64 v[2:3], s[22:23], 0, v[0:1]
	v_lshl_add_u64 v[0:1], s[24:25], 0, v[0:1]
	v_lshl_add_u64 v[26:27], v[2:3], 0, v[152:153]
	v_lshl_add_u64 v[28:29], v[0:1], 0, v[152:153]
	global_load_dwordx4 v[0:3], v[164:165], off
	v_lshl_add_u64 v[4:5], v[164:165], 0, s[8:9]
	global_load_dwordx4 v[4:7], v[4:5], off
	v_lshl_add_u64 v[8:9], v[164:165], 0, s[4:5]
	global_load_dwordx4 v[8:11], v[8:9], off
	v_lshl_add_u64 v[12:13], v[164:165], 0, s[90:91]
	global_load_dwordx4 v[12:15], v[12:13], off
	global_load_dwordx4 v[16:19], v[166:167], off
	v_lshl_add_u64 v[20:21], v[166:167], 0, s[8:9]
	global_load_dwordx4 v[20:23], v[20:21], off
	v_lshl_add_u64 v[30:31], v[164:165], 0, 64
	global_load_dwordx4 v[48:51], v[30:31], off
	v_lshl_add_u64 v[30:31], v[164:165], 0, s[0:1]
	global_load_dwordx4 v[56:59], v[30:31], off
	s_mov_b64 s[18:19], 0x40040
	v_lshl_add_u64 v[30:31], v[164:165], 0, s[18:19]
	global_load_dwordx4 v[60:63], v[30:31], off
	s_mov_b64 s[18:19], 0x60040
	v_lshl_add_u64 v[30:31], v[164:165], 0, s[18:19]
	global_load_dwordx4 v[68:71], v[30:31], off
	v_lshl_add_u64 v[32:33], v[166:167], 0, 64
	global_load_dwordx4 v[72:75], v[32:33], off
	v_lshl_add_u64 v[30:31], v[166:167], 0, s[0:1]
	global_load_dwordx4 v[80:83], v[30:31], off
	s_barrier
	s_waitcnt vmcnt(6)
	s_movk_i32 s2, 0x50
	v_add_u32_e32 v36, 4, v24
	v_and_b32_e32 v36, 8, v36
	v_lshlrev_b32_e32 v36, 1, v36
	v_xor_b32_e32 v36, v152, v36
	v_mad_u32_u24 v168, v24, s2, v36
	ds_write_b128 v168, v[0:3]
	ds_write_b128 v168, v[4:7] offset:5120
	ds_write_b128 v168, v[8:11] offset:10240
	ds_write_b128 v168, v[12:15] offset:15360
	ds_write_b128 v168, v[16:19] offset:40960
	ds_write_b128 v168, v[20:23] offset:46080
	v_and_b32_e32 v0, 0x4f, v34
	v_and_b32_e32 v1, 0xfffff8f, v34
	v_mul_u32_u24_e32 v2, 40, v0
	v_and_b32_e32 v0, 48, v34
	v_add_u32_e32 v36, 4, v34
	v_and_b32_e32 v36, 8, v36
	v_lshlrev_b32_e32 v36, 1, v36
	v_xor_b32_e32 v0, v0, v36
	v_lshl_add_u32 v169, v2, 1, v0
	v_mad_u32_u24 v172, v1, s2, v0
	v_mov_b32_e32 v0, 0
	v_cndmask_b32_e64 v157, v27, v165, s[10:11]
	v_cndmask_b32_e64 v152, v26, v164, s[10:11]
	v_cndmask_b32_e64 v159, v29, v167, s[10:11]
	v_cndmask_b32_e64 v170, v28, v166, s[10:11]
	s_mov_b32 s17, 0
	s_movk_i32 s15, 0xfc40
	v_mov_b32_e32 v1, v0
	v_mov_b32_e32 v2, v0
	v_mov_b32_e32 v3, v0
	v_mov_b32_e32 v4, v0
	v_mov_b32_e32 v5, v0
	v_mov_b32_e32 v6, v0
	v_mov_b32_e32 v7, v0
	v_mov_b32_e32 v8, v0
	v_mov_b32_e32 v9, v0
	v_mov_b32_e32 v10, v0
	v_mov_b32_e32 v11, v0
	v_mov_b32_e32 v12, v0
	v_mov_b32_e32 v13, v0
	v_mov_b32_e32 v14, v0
	v_mov_b32_e32 v15, v0
	v_mov_b32_e32 v16, v0
	v_mov_b32_e32 v17, v0
	v_mov_b32_e32 v18, v0
	v_mov_b32_e32 v19, v0
	v_mov_b32_e32 v20, v0
	v_mov_b32_e32 v21, v0
	v_mov_b32_e32 v22, v0
	v_mov_b32_e32 v23, v0
	v_mov_b32_e32 v24, v0
	v_mov_b32_e32 v25, v0
	v_mov_b32_e32 v26, v0
	v_mov_b32_e32 v27, v0
	v_mov_b32_e32 v28, v0
	v_mov_b32_e32 v29, v0
	v_mov_b32_e32 v30, v0
	v_mov_b32_e32 v31, v0
	v_mov_b32_e32 v32, v0
	v_mov_b32_e32 v33, v0
	v_mov_b32_e32 v34, v0
	v_mov_b32_e32 v35, v0
	v_mov_b32_e32 v36, v0
	v_mov_b32_e32 v37, v0
	v_mov_b32_e32 v38, v0
	v_mov_b32_e32 v39, v0
	v_mov_b32_e32 v40, v0
	v_mov_b32_e32 v41, v0
	v_mov_b32_e32 v42, v0
	v_mov_b32_e32 v43, v0
	v_mov_b32_e32 v44, v0
	v_mov_b32_e32 v45, v0
	v_mov_b32_e32 v46, v0
	v_mov_b32_e32 v47, v0
	v_mov_b32_e32 v52, v0
	v_mov_b32_e32 v53, v0
	v_mov_b32_e32 v54, v0
	v_mov_b32_e32 v55, v0
	v_mov_b32_e32 v64, v0
	v_mov_b32_e32 v65, v0
	v_mov_b32_e32 v66, v0
	v_mov_b32_e32 v67, v0
	v_mov_b32_e32 v76, v0
	v_mov_b32_e32 v77, v0
	v_mov_b32_e32 v78, v0
	v_mov_b32_e32 v79, v0
	v_mov_b32_e32 v84, v0
	v_mov_b32_e32 v85, v0
	v_mov_b32_e32 v86, v0
	v_mov_b32_e32 v87, v0
	v_mov_b32_e32 v88, v0
	v_mov_b32_e32 v89, v0
	v_mov_b32_e32 v90, v0
	v_mov_b32_e32 v91, v0
	v_mov_b32_e32 v92, v0
	v_mov_b32_e32 v93, v0
	v_mov_b32_e32 v94, v0
	v_mov_b32_e32 v95, v0
	v_mov_b32_e32 v96, v0
	v_mov_b32_e32 v97, v0
	v_mov_b32_e32 v98, v0
	v_mov_b32_e32 v99, v0
	v_mov_b32_e32 v100, v0
	v_mov_b32_e32 v101, v0
	v_mov_b32_e32 v102, v0
	v_mov_b32_e32 v103, v0
	v_mov_b32_e32 v104, v0
	v_mov_b32_e32 v105, v0
	v_mov_b32_e32 v106, v0
	v_mov_b32_e32 v107, v0
	v_mov_b32_e32 v108, v0
	v_mov_b32_e32 v109, v0
	v_mov_b32_e32 v110, v0
	v_mov_b32_e32 v111, v0
	v_mov_b32_e32 v112, v0
	v_mov_b32_e32 v113, v0
	v_mov_b32_e32 v114, v0
	v_mov_b32_e32 v115, v0
	v_mov_b32_e32 v116, v0
	v_mov_b32_e32 v117, v0
	v_mov_b32_e32 v118, v0
	v_mov_b32_e32 v119, v0
	v_mov_b32_e32 v120, v0
	v_mov_b32_e32 v121, v0
	v_mov_b32_e32 v122, v0
	v_mov_b32_e32 v123, v0
	v_mov_b32_e32 v124, v0
	v_mov_b32_e32 v125, v0
	v_mov_b32_e32 v126, v0
	v_mov_b32_e32 v127, v0
	v_mov_b32_e32 v128, v0
	v_mov_b32_e32 v129, v0
	v_mov_b32_e32 v130, v0
	v_mov_b32_e32 v131, v0
	v_mov_b32_e32 v132, v0
	v_mov_b32_e32 v133, v0
	v_mov_b32_e32 v134, v0
	v_mov_b32_e32 v135, v0
	v_mov_b32_e32 v136, v0
	v_mov_b32_e32 v137, v0
	v_mov_b32_e32 v138, v0
	v_mov_b32_e32 v139, v0
	v_mov_b32_e32 v140, v0
	v_mov_b32_e32 v141, v0
	v_mov_b32_e32 v142, v0
	v_mov_b32_e32 v143, v0
	v_mov_b32_e32 v144, v0
	v_mov_b32_e32 v145, v0
	v_mov_b32_e32 v146, v0
	v_mov_b32_e32 v147, v0
	v_mov_b32_e32 v148, v0
	v_mov_b32_e32 v149, v0
	v_mov_b32_e32 v150, v0
	v_mov_b32_e32 v151, v0
	s_waitcnt lgkmcnt(0)
	s_barrier

; __device__ __forceinline__ int opaque_tid() { int t = threadIdx.x; asm volatile("" : "+v"(t)); return t; }
;   __device__ __forceinline__ float* gl() const { return (float*)(b + L::o_gl); }
; template <int BN, bool SWAP> ...
;     ...
;   const int tid = opaque_tid(), lane = tid & 63, wave = tid >> 6;
;   const int wr = wave >> 1, wc = wave & 1, c15 = lane & 15, g = lane >> 4;
;   bfu* As = sm;
;   bfu* Bs = sm + 2 * 128 * 72;
;   const int lrow = tid >> 3, lch = (tid & 7) * 8;
;   const bfu* Ap = A + (size_t)lrow * lda + lch;
;   const bfu* Bp = B + (size_t)lrow * ldb + lch;
;   int brow = lrow;
;   if (SWAP) {
;     if (NJ == 4) brow = ((lrow & 12) << 2) | ((lrow >> 2) & 4) | (lrow & 3);
;     else brow = ((lrow & 4) << 2) | ((lrow >> 1) & 12) | (lrow & 3);
;   }
;   const int nk = K >> 6;
;   const bool chain = (An != nullptr);
;   const bfu* Apn = chain ? (An + (size_t)lrow * ldan + lch) : Ap;
;   const bfu* Bpn = chain ? (Bn + (size_t)lrow * ldbn + lch) : Bp;
;     ...
;   gl(ra0, rb0, 0);
;   gl(ra1, rb1, 1);
;   __syncthreads();
;   wt(ra0, rb0);
;   st(ra0, rb0, 0);
;   __syncthreads();
;   for (int kt = 0; kt < nk; kt += 2) {
;     gl(ra0, rb0, kt + 2);
;     comp(0, [&]() { wt(ra1, rb1); st(ra1, rb1, 1); });
;     __syncthreads();
;     gl(ra1, rb1, kt + 3);
;     comp(1, [&]() { wt(ra0, rb0); st(ra0, rb0, 0); });
.LBB0_460:
	s_lshl_b32 s22, s31, 10
	s_add_i32 s0, s34, s22
	s_ashr_i32 s1, s0, 31
	s_lshl_b64 s[0:1], s[0:1], 11
	s_add_u32 s0, s26, s0
	s_addc_u32 s1, s27, s1
	v_mov_b32_e32 v54, v174
	s_add_u32 s12, s35, s22
	s_addc_u32 s13, s36, 0
	v_ashrrev_i32_e32 v52, 3, v54
	v_ashrrev_i32_e32 v53, 31, v52
	s_add_u32 s24, s22, s16
	v_lshlrev_b64 v[2:3], 11, v[52:53]
	v_lshlrev_b32_e32 v6, 4, v54
	s_addc_u32 s25, 0, s17
	v_lshl_add_u64 v[4:5], s[20:21], 0, v[2:3]
	v_and_b32_e32 v152, 0x70, v6
	v_lshl_add_u64 v[2:3], s[0:1], 0, v[2:3]
	s_lshl_b64 s[24:25], s[24:25], 10
	v_lshl_add_u64 v[50:51], v[2:3], 0, v[152:153]
	v_lshlrev_b32_e32 v2, 2, v52
	v_lshrrev_b32_e32 v3, 1, v52
	s_add_u32 s24, s28, s24
	v_lshl_add_u64 v[48:49], v[4:5], 0, v[152:153]
	v_and_b32_e32 v2, 16, v2
	v_and_b32_e32 v3, 12, v3
	v_and_b32_e32 v4, 3, v52
	s_addc_u32 s25, s29, s25
	v_lshlrev_b64 v[0:1], 10, v[52:53]
	v_or3_b32 v62, v4, v3, v2
	v_lshlrev_b64 v[2:3], 12, v[52:53]
	v_lshl_add_u64 v[2:3], s[12:13], 0, v[2:3]
	v_lshl_add_u64 v[0:1], s[24:25], 0, v[0:1]
	v_lshl_add_u64 v[56:57], v[2:3], 0, v[152:153]
	v_lshl_add_u64 v[58:59], v[0:1], 0, v[152:153]
	global_load_dwordx4 v[0:3], v[48:49], off
	v_lshl_add_u64 v[4:5], v[48:49], 0, s[76:77]
	global_load_dwordx4 v[4:7], v[4:5], off
	v_lshl_add_u64 v[8:9], v[48:49], 0, s[8:9]
	global_load_dwordx4 v[12:15], v[8:9], off
	v_lshl_add_u64 v[8:9], v[48:49], 0, s[78:79]
	global_load_dwordx4 v[20:23], v[8:9], off
	global_load_dwordx4 v[32:35], v[50:51], off
	v_lshl_add_u64 v[8:9], v[50:51], 0, s[76:77]
	global_load_dwordx4 v[44:47], v[8:9], off
	v_lshl_add_u64 v[8:9], v[48:49], 0, s[80:81]
	s_mov_b64 s[0:1], 0x10080
	global_load_dwordx4 v[8:11], v[8:9], off
	v_lshl_add_u64 v[16:17], v[48:49], 0, s[0:1]
	global_load_dwordx4 v[16:19], v[16:17], off
	v_lshl_add_u64 v[24:25], v[48:49], 0, s[82:83]
	global_load_dwordx4 v[24:27], v[24:25], off
	v_lshl_add_u64 v[28:29], v[48:49], 0, s[84:85]
	v_lshl_add_u64 v[36:37], v[50:51], 0, s[80:81]
	global_load_dwordx4 v[28:31], v[28:29], off
	global_load_dwordx4 v[36:39], v[36:37], off
	v_lshl_add_u64 v[40:41], v[50:51], 0, s[0:1]
	global_load_dwordx4 v[40:43], v[40:41], off
	s_barrier
	s_waitcnt vmcnt(6)
	v_add_u32_e32 v164, 4, v52
	v_and_b32_e32 v164, 8, v164
	v_lshlrev_b32_e32 v164, 1, v164
	v_xor_b32_e32 v164, v152, v164
	v_mad_u32_u24 v60, v52, s89, v164
	v_and_b32_e32 v55, 15, v54
	ds_write_b128 v60, v[0:3]
	ds_write_b128 v60, v[4:7] offset:4608
	ds_write_b128 v60, v[12:15] offset:9216
	ds_write_b128 v60, v[20:23] offset:13824
	v_lshrrev_b32_e32 v1, 1, v54
	v_and_or_b32 v2, v1, s74, v55
	v_and_b32_e32 v0, 48, v54
	v_add_u32_e32 v164, 4, v62
	v_and_b32_e32 v164, 8, v164
	v_lshlrev_b32_e32 v164, 1, v164
	v_xor_b32_e32 v164, v152, v164
	v_mad_u32_u24 v61, v62, s89, v164
	v_add_u32_e32 v164, 4, v54
	v_and_b32_e32 v164, 8, v164
	v_lshlrev_b32_e32 v164, 1, v164
	v_xor_b32_e32 v0, v0, v164
	v_mad_u32_u24 v62, v2, s89, v0
	v_and_or_b32 v1, v1, 32, v55
	v_mul_u32_u24_e32 v1, 0x48, v1
	s_mov_b32 s23, s3
	ds_write_b128 v61, v[32:35] offset:36864
	ds_write_b128 v61, v[44:47] offset:41472
	v_lshl_add_u32 v63, v1, 1, v0
	s_mov_b32 s41, 0
	s_mov_b32 s0, 0
	v_mov_b32_e32 v0, 0
	v_mov_b32_e32 v1, v135
	v_mov_b32_e32 v2, v135
	v_mov_b32_e32 v3, v135
	v_mov_b32_e32 v4, 0
	v_mov_b32_e32 v5, v135
	v_mov_b32_e32 v6, v135
	v_mov_b32_e32 v7, v135
	v_mov_b32_e32 v12, 0
	v_mov_b32_e32 v13, v135
	v_mov_b32_e32 v14, v135
	v_mov_b32_e32 v15, v135
	v_mov_b32_e32 v20, 0
	v_mov_b32_e32 v21, v135
	v_mov_b32_e32 v22, v135
	v_mov_b32_e32 v23, v135
	v_mov_b32_e32 v32, 0
	v_mov_b32_e32 v33, v135
	v_mov_b32_e32 v34, v135
	v_mov_b32_e32 v35, v135
	v_mov_b32_e32 v44, 0
	v_mov_b32_e32 v45, v135
	v_mov_b32_e32 v46, v135
	v_mov_b32_e32 v47, v135
	v_mov_b32_e32 v52, 0
	v_mov_b32_e32 v53, v135
	v_mov_b32_e32 v54, v135
	v_mov_b32_e32 v55, v135
	v_mov_b32_e32 v64, 0
	v_mov_b32_e32 v65, v135
	v_mov_b32_e32 v66, v135
	v_mov_b32_e32 v67, v135
	s_waitcnt lgkmcnt(0)
	s_barrier
.LBB0_461:
	s_add_i32 s42, s0, 2
	s_cmp_lt_u32 s0, 14
	s_cselect_b64 vcc, -1, 0
	s_add_i32 s1, s41, 0xfffffc80
	s_add_i32 s43, s41, 0x80
	s_and_b64 s[44:45], vcc, exec
	s_cselect_b32 s44, s43, s1
	s_mov_b32 s45, s3
	v_cndmask_b32_e32 v69, v57, v49, vcc
	v_cndmask_b32_e32 v68, v56, v48, vcc
	v_cndmask_b32_e32 v71, v59, v51, vcc
	v_cndmask_b32_e32 v70, v58, v50, vcc
	s_cselect_b32 s1, s33, 0x800
	s_cselect_b32 s2, 0x10000, s88
	s_lshl_b64 s[44:45], s[44:45], 1
	v_lshl_add_u64 v[128:129], v[70:71], 0, s[44:45]
	v_lshl_add_u64 v[80:81], v[68:69], 0, s[44:45]
	s_lshl_b32 s44, s1, 6
	s_mov_b32 s45, s3
	v_lshl_add_u64 v[72:73], v[80:81], 0, s[44:45]
	s_lshl_b32 s44, s1, 7
	global_load_dwordx4 v[68:71], v[80:81], off
	s_and_b64 vcc, vcc, exec
	global_load_dwordx4 v[72:75], v[72:73], off
	v_lshl_add_u64 v[76:77], v[80:81], 0, s[44:45]
	s_cselect_b32 s44, s75, 0x60000
	global_load_dwordx4 v[76:79], v[76:77], off
	v_lshl_add_u64 v[80:81], v[80:81], 0, s[44:45]
	global_load_dwordx4 v[80:83], v[80:81], off
	global_load_dwordx4 v[84:87], v[128:129], off
	v_lshl_add_u64 v[128:129], v[128:129], 0, s[2:3]
	global_load_dwordx4 v[128:131], v[128:129], off
	ds_read_b128 v[136:139], v62
	ds_read_b128 v[140:143], v62 offset:2304
	ds_read_b128 v[144:147], v62 offset:4608
	ds_read_b128 v[148:151], v62 offset:6912
	ds_read_b128 v[164:167], v63 offset:36864
	ds_read_b128 v[168:171], v63 offset:39168
	s_waitcnt vmcnt(6)
	ds_write_b128 v60, v[8:11] offset:18432
	ds_write_b128 v60, v[16:19] offset:23040
	ds_write_b128 v60, v[24:27] offset:27648
	ds_write_b128 v60, v[28:31] offset:32256
	ds_write_b128 v61, v[36:39] offset:46080
	ds_write_b128 v61, v[40:43] offset:50688
	s_setprio 1
	s_waitcnt lgkmcnt(7)
; #define MFMA16(a, b, c) __builtin_amdgcn_mfma_f32_16x16x32_bf16((a), (b), (c), 0, 0, 0)
;   __device__ __forceinline__ float* gl() const { return (float*)(b + L::o_gl); }
; template <int BN, bool SWAP> ...
;     ...
;   auto comp = [&](int buf, auto&& mid) {
;     const bfu* as = As + buf * 128 * 72 + (wr * 64 + c15) * 72 + g * 8;
;     const bfu* bs = Bs + buf * BN * 72 + (wc * (BN / 2) + c15) * 72 + g * 8;
;     {
;       bf16x8 a0[4], b0[NJ];
; #pragma unroll
;       for (int i = 0; i < 4; ++i) a0[i] = *(const bf16x8*)(as + i * 16 * 72);
; #pragma unroll
;       for (int j = 0; j < NJ; ++j) b0[j] = *(const bf16x8*)(bs + j * 16 * 72);
;       mid();
;       __builtin_amdgcn_s_setprio(1);
; #pragma unroll
;       for (int i = 0; i < 4; ++i)
; #pragma unroll
;         for (int j = 0; j < NJ; ++j) acc[i][j] = SWAP ? MFMA16(b0[j], a0[i], acc[i][j]) : MFMA16(a0[i], b0[j], acc[i][j]);
;       __builtin_amdgcn_s_setprio(0);
;     }
;     {
;       bf16x8 a1[4], b1[NJ];
; #pragma unroll
;       for (int i = 0; i < 4; ++i) a1[i] = *(const bf16x8*)(as + i * 16 * 72 + 32);
; #pragma unroll
;       for (int j = 0; j < NJ; ++j) b1[j] = *(const bf16x8*)(bs + j * 16 * 72 + 32);
;       __builtin_amdgcn_s_setprio(1);
; #pragma unroll
;       for (int i = 0; i < 4; ++i)
; #pragma unroll
;         for (int j = 0; j < NJ; ++j) acc[i][j] = SWAP ? MFMA16(b1[j], a1[i], acc[i][j]) : MFMA16(a1[i], b1[j], acc[i][j]);
;       __builtin_amdgcn_s_setprio(0);
;     }
;   };
;   gl(ra0, rb0, 0);
;   gl(ra1, rb1, 1);
;   __syncthreads();
;   wt(ra0, rb0);
;   st(ra0, rb0, 0);
;   __syncthreads();
;   for (int kt = 0; kt < nk; kt += 2) {
;     gl(ra0, rb0, kt + 2);
;     comp(0, [&]() { wt(ra1, rb1); st(ra1, rb1, 1); });
;     __syncthreads();
;     gl(ra1, rb1, kt + 3);
;     comp(1, [&]() { wt(ra0, rb0); st(ra0, rb0, 0); });
;     __syncthreads();
	v_mfma_f32_16x16x32_bf16 v[8:11], v[164:167], v[136:139], v[64:67]
	s_waitcnt lgkmcnt(6)
	v_mfma_f32_16x16x32_bf16 v[16:19], v[168:171], v[136:139], v[52:55]
	v_mfma_f32_16x16x32_bf16 v[24:27], v[164:167], v[140:143], v[44:47]
	v_mfma_f32_16x16x32_bf16 v[28:31], v[168:171], v[140:143], v[32:35]
	v_mfma_f32_16x16x32_bf16 v[20:23], v[164:167], v[144:147], v[20:23]
	v_mfma_f32_16x16x32_bf16 v[12:15], v[168:171], v[144:147], v[12:15]
	v_mfma_f32_16x16x32_bf16 v[4:7], v[164:167], v[148:151], v[4:7]
	v_mfma_f32_16x16x32_bf16 v[0:3], v[168:171], v[148:151], v[0:3]
	s_setprio 0
	ds_read_b128 v[32:35], v62 offset:64
	ds_read_b128 v[36:39], v62 offset:2368
	ds_read_b128 v[40:43], v62 offset:4672
	ds_read_b128 v[44:47], v62 offset:6976
	ds_read_b128 v[52:55], v63 offset:36928
	ds_read_b128 v[64:67], v63 offset:39232
	s_setprio 1
	s_waitcnt lgkmcnt(1)
	v_mfma_f32_16x16x32_bf16 v[136:139], v[52:55], v[32:35], v[8:11]
	s_waitcnt lgkmcnt(0)
	v_mfma_f32_16x16x32_bf16 v[32:35], v[64:67], v[32:35], v[16:19]
	v_mfma_f32_16x16x32_bf16 v[20:23], v[52:55], v[40:43], v[20:23]
	v_mfma_f32_16x16x32_bf16 v[12:15], v[64:67], v[40:43], v[12:15]
	v_mfma_f32_16x16x32_bf16 v[4:7], v[52:55], v[44:47], v[4:7]
	v_mfma_f32_16x16x32_bf16 v[0:3], v[64:67], v[44:47], v[0:3]
	v_mfma_f32_16x16x32_bf16 v[140:143], v[52:55], v[36:39], v[24:27]
	v_mfma_f32_16x16x32_bf16 v[144:147], v[64:67], v[36:39], v[28:31]
	s_setprio 0
	s_cmp_lt_u32 s0, 13
	s_cselect_b64 s[0:1], -1, 0
	s_and_b64 s[44:45], s[0:1], exec
	s_cselect_b32 s44, 0xc0, s86
	v_cndmask_b32_e64 v9, v57, v49, s[0:1]
	v_cndmask_b32_e64 v8, v56, v48, s[0:1]
	v_cndmask_b32_e64 v11, v59, v51, s[0:1]
	v_cndmask_b32_e64 v10, v58, v50, s[0:1]
	s_cselect_b32 s1, s33, 0x800
	s_cselect_b32 s2, 0x10000, s88
	s_cselect_b32 s0, s75, 0x60000
	s_add_i32 s44, s44, s41
	s_mov_b32 s45, s3
	s_lshl_b64 s[44:45], s[44:45], 1
	v_lshl_add_u64 v[40:41], v[10:11], 0, s[44:45]
	v_lshl_add_u64 v[28:29], v[8:9], 0, s[44:45]
	s_lshl_b32 s44, s1, 6
	s_mov_b32 s45, s3
	s_barrier
	global_load_dwordx4 v[8:11], v[28:29], off
	v_lshl_add_u64 v[16:17], v[28:29], 0, s[44:45]
	s_lshl_b32 s44, s1, 7
	global_load_dwordx4 v[16:19], v[16:17], off
	v_lshl_add_u64 v[24:25], v[28:29], 0, s[44:45]
	s_mov_b32 s1, s3
	global_load_dwordx4 v[24:27], v[24:25], off
	v_lshl_add_u64 v[28:29], v[28:29], 0, s[0:1]
	global_load_dwordx4 v[28:31], v[28:29], off
	global_load_dwordx4 v[36:39], v[40:41], off
	v_lshl_add_u64 v[40:41], v[40:41], 0, s[2:3]
	global_load_dwordx4 v[40:43], v[40:41], off
	ds_read_b128 v[44:47], v62 offset:18432
	ds_read_b128 v[52:55], v62 offset:20736
	ds_read_b128 v[64:67], v62 offset:23040
	ds_read_b128 v[148:151], v62 offset:25344
	ds_read_b128 v[164:167], v63 offset:46080
	ds_read_b128 v[168:171], v63 offset:48384
	s_waitcnt vmcnt(6)
	ds_write_b128 v60, v[68:71]
	ds_write_b128 v60, v[72:75] offset:4608
	ds_write_b128 v60, v[76:79] offset:9216
	ds_write_b128 v60, v[80:83] offset:13824
	ds_write_b128 v61, v[84:87] offset:36864
	ds_write_b128 v61, v[128:131] offset:41472
	s_setprio 1
	s_waitcnt lgkmcnt(7)
	v_mfma_f32_16x16x32_bf16 v[68:71], v[164:167], v[44:47], v[136:139]
	s_waitcnt lgkmcnt(6)
	v_mfma_f32_16x16x32_bf16 v[32:35], v[168:171], v[44:47], v[32:35]
	v_mfma_f32_16x16x32_bf16 v[44:47], v[164:167], v[52:55], v[140:143]
	v_mfma_f32_16x16x32_bf16 v[20:23], v[164:167], v[64:67], v[20:23]
	v_mfma_f32_16x16x32_bf16 v[12:15], v[168:171], v[64:67], v[12:15]
	v_mfma_f32_16x16x32_bf16 v[4:7], v[164:167], v[148:151], v[4:7]
	v_mfma_f32_16x16x32_bf16 v[0:3], v[168:171], v[148:151], v[0:3]
	v_mfma_f32_16x16x32_bf16 v[72:75], v[168:171], v[52:55], v[144:147]
	s_setprio 0
	ds_read_b128 v[52:55], v62 offset:18496
	ds_read_b128 v[76:79], v62 offset:20800
	ds_read_b128 v[80:83], v62 offset:23104
	ds_read_b128 v[84:87], v62 offset:25408
	ds_read_b128 v[128:131], v63 offset:46144
	ds_read_b128 v[136:139], v63 offset:48448
	s_setprio 1
	s_waitcnt lgkmcnt(1)
	v_mfma_f32_16x16x32_bf16 v[64:67], v[128:131], v[52:55], v[68:71]
	s_waitcnt lgkmcnt(0)
	v_mfma_f32_16x16x32_bf16 v[52:55], v[136:139], v[52:55], v[32:35]
	v_mfma_f32_16x16x32_bf16 v[44:47], v[128:131], v[76:79], v[44:47]
	v_mfma_f32_16x16x32_bf16 v[32:35], v[136:139], v[76:79], v[72:75]
	v_mfma_f32_16x16x32_bf16 v[20:23], v[128:131], v[80:83], v[20:23]
	v_mfma_f32_16x16x32_bf16 v[12:15], v[136:139], v[80:83], v[12:15]
	v_mfma_f32_16x16x32_bf16 v[4:7], v[128:131], v[84:87], v[4:7]
	v_mfma_f32_16x16x32_bf16 v[0:3], v[136:139], v[84:87], v[0:3]
	s_setprio 0
	s_mov_b32 s41, s43
	s_mov_b32 s0, s42
	s_barrier
; template <int BN, bool SWAP> ...
;     ...
;   const bfu* Apn = chain ? (An + (size_t)lrow * ldan + lch) : Ap;
;   const bfu* Bpn = chain ? (Bn + (size_t)lrow * ldbn + lch) : Bp;
;   auto gl = [&](bf16x8 (&ra)[4], bf16x8 (&rb)[NJ], int kt) {
;     const bool nx = (kt >= nk);
;     const bfu* pa = nx ? (chain ? Apn + (kt - nk) * 64 : Ap + (nk - 1) * 64) : Ap + kt * 64;
;     const bfu* pb = nx ? (chain ? Bpn + (kt - nk) * 64 : Bp + (nk - 1) * 64) : Bp + kt * 64;
;     const size_t sa = (nx && chain) ? (size_t)ldan : (size_t)lda, sb = (nx && chain) ? (size_t)ldbn : (size_t)ldb;
; #pragma unroll
;     for (int q = 0; q < 4; ++q) ra[q] = gld16(pa + (size_t)(32 * q) * sa);
; #pragma unroll
;     for (int q = 0; q < NJ; ++q) rb[q] = gld16(pb + (size_t)(32 * q) * sb);
;   };
;   auto wt = [&](bf16x8 (&ra)[4], bf16x8 (&rb)[NJ]) {
;     if (NJ == 4) asm volatile("s_waitcnt vmcnt(8)" : "+v"(ra[0]), "+v"(ra[1]), "+v"(ra[2]), "+v"(ra[3]), "+v"(rb[0]), "+v"(rb[1]), "+v"(rb[NJ - 2]), "+v"(rb[NJ - 1]) : : "memory");
;     else asm volatile("s_waitcnt vmcnt(6)" : "+v"(ra[0]), "+v"(ra[1]), "+v"(ra[2]), "+v"(ra[3]), "+v"(rb[0]), "+v"(rb[1]) : : "memory");
;   };
;   auto st = [&](const bf16x8 (&ra)[4], const bf16x8 (&rb)[NJ], int buf) {
; #pragma unroll
;     for (int q = 0; q < 4; ++q) *(bf16x8*)(As + (buf * 128 + lrow + 32 * q) * 72 + lch) = ra[q];
; #pragma unroll
;     for (int q = 0; q < NJ; ++q) *(bf16x8*)(Bs + (buf * BN + brow + ((SWAP && NJ == 4) ? (8 * (q & 1) + 64 * (q >> 1)) : 32 * q)) * 72 + lch) = rb[q];
;   };
;   auto comp = [&](int buf, auto&& mid) {
;     const bfu* as = As + buf * 128 * 72 + (wr * 64 + c15) * 72 + g * 8;
;     const bfu* bs = Bs + buf * BN * 72 + (wc * (BN / 2) + c15) * 72 + g * 8;
;     {
;       bf16x8 a0[4], b0[NJ];
; #pragma unroll
;       for (int i = 0; i < 4; ++i) a0[i] = *(const bf16x8*)(as + i * 16 * 72);
; #pragma unroll
; template <int G>
; __device__ __forceinline__ void p4(const Params& P, const Ptrs<G>& w, int pass, int layer, bfu* sm, const XcdInfo& xi) {
;     ...
;       const bfu* An; const bfu* Bn;
;       if (b < 3) { An = Ag; Bn = Wl + (size_t)(7808 + (b + 1) * 1024 + n0) * 1024; }
;       else if (has_next) { An = w.xb() + (size_t)(mt2 * 128) * 1024; Bn = Wl + (size_t)(7808 + nt2 * 64) * 1024; }
;       else { An = nullptr; Bn = nullptr; }
;       gemm_core<64, true>(Apb, 2048, Bpb, 512, 512, Pa, sm, An, 1024, Bn, 1024);
	s_cbranch_vccnz .LBB0_461
	v_mov_b32_e32 v70, v174
	s_waitcnt vmcnt(0)
	s_add_i32 s0, s19, s22
	v_ashrrev_i32_e32 v60, 3, v70
	v_ashrrev_i32_e32 v61, 31, v60
	v_lshlrev_b64 v[8:9], 12, v[60:61]
	v_lshlrev_b32_e32 v10, 4, v70
	s_ashr_i32 s1, s0, 31
	v_lshl_add_u64 v[8:9], s[12:13], 0, v[8:9]
	v_and_b32_e32 v152, 0x70, v10
	s_lshl_b64 s[0:1], s[0:1], 11
	v_lshl_add_u64 v[128:129], v[8:9], 0, v[152:153]
	v_lshlrev_b64 v[8:9], 10, v[60:61]
	s_add_u32 s0, s26, s0
	v_lshl_add_u64 v[8:9], s[24:25], 0, v[8:9]
	s_addc_u32 s1, s27, s1
	v_lshl_add_u64 v[130:131], v[8:9], 0, v[152:153]
	v_lshlrev_b32_e32 v8, 2, v60
	v_lshrrev_b32_e32 v9, 1, v60
	s_cmp_eq_u32 s31, 3
	v_and_b32_e32 v8, 16, v8
	v_and_b32_e32 v9, 12, v9
	v_and_b32_e32 v10, 3, v60
	s_cselect_b32 s1, s37, s1
	s_cselect_b32 s0, s38, s0
	s_cselect_b32 s43, s39, s21
	s_cselect_b32 s42, s40, s20
	v_or3_b32 v138, v10, v9, v8
	v_lshlrev_b64 v[8:9], 11, v[60:61]
	s_cmp_eq_u64 s[42:43], 0
	v_lshl_add_u64 v[10:11], s[42:43], 0, v[8:9]
	v_lshl_add_u64 v[8:9], s[0:1], 0, v[8:9]
	v_lshl_add_u64 v[10:11], v[10:11], 0, v[152:153]
	s_cselect_b64 s[12:13], -1, 0
	v_lshl_add_u64 v[8:9], v[8:9], 0, v[152:153]
	v_cndmask_b32_e64 v91, v11, v129, s[12:13]
	v_cndmask_b32_e64 v132, v10, v128, s[12:13]
	v_cndmask_b32_e64 v93, v9, v131, s[12:13]
	v_cndmask_b32_e64 v134, v8, v130, s[12:13]
	global_load_dwordx4 v[8:11], v[128:129], off
	v_lshl_add_u64 v[16:17], v[128:129], 0, s[8:9]
	global_load_dwordx4 v[16:19], v[16:17], off
	v_lshl_add_u64 v[24:25], v[128:129], 0, s[4:5]
	global_load_dwordx4 v[28:31], v[24:25], off
	v_lshl_add_u64 v[24:25], v[128:129], 0, s[90:91]
	global_load_dwordx4 v[40:43], v[24:25], off
	global_load_dwordx4 v[48:51], v[130:131], off
	v_lshl_add_u64 v[24:25], v[130:131], 0, s[92:93]
	global_load_dwordx4 v[56:59], v[24:25], off
	v_lshl_add_u64 v[24:25], v[128:129], 0, s[80:81]
	global_load_dwordx4 v[24:27], v[24:25], off
	v_lshl_add_u64 v[36:37], v[128:129], 0, s[82:83]
	global_load_dwordx4 v[36:39], v[36:37], off
	s_mov_b64 s[0:1], 0x40080
	v_lshl_add_u64 v[68:69], v[128:129], 0, s[0:1]
	global_load_dwordx4 v[72:75], v[68:69], off
	s_mov_b64 s[0:1], 0x60080
	v_lshl_add_u64 v[68:69], v[128:129], 0, s[0:1]
	global_load_dwordx4 v[76:79], v[68:69], off
	v_lshl_add_u64 v[62:63], v[130:131], 0, s[80:81]
	global_load_dwordx4 v[80:83], v[62:63], off
	s_mov_b64 s[0:1], 0x8080
	v_lshl_add_u64 v[62:63], v[130:131], 0, s[0:1]
	global_load_dwordx4 v[84:87], v[62:63], off
	s_barrier
	s_waitcnt vmcnt(6)
	v_add_u32_e32 v198, 4, v60
	v_and_b32_e32 v198, 8, v198
	v_lshlrev_b32_e32 v198, 1, v198
	v_xor_b32_e32 v198, v152, v198
	v_mad_u32_u24 v136, v60, s89, v198
	v_and_b32_e32 v71, 15, v70
	ds_write_b128 v136, v[8:11]
	ds_write_b128 v136, v[16:19] offset:4608
	ds_write_b128 v136, v[28:31] offset:9216
	ds_write_b128 v136, v[40:43] offset:13824
	v_lshrrev_b32_e32 v9, 1, v70
	v_and_or_b32 v10, v9, s74, v71
	v_and_b32_e32 v8, 48, v70
	v_add_u32_e32 v198, 4, v138
	v_and_b32_e32 v198, 8, v198
	v_lshlrev_b32_e32 v198, 1, v198
	v_xor_b32_e32 v198, v152, v198
	v_mad_u32_u24 v137, v138, s89, v198
	v_add_u32_e32 v198, 4, v70
	v_and_b32_e32 v198, 8, v198
	v_lshlrev_b32_e32 v198, 1, v198
	v_xor_b32_e32 v8, v8, v198
	v_mad_u32_u24 v138, v10, s89, v8
	v_and_or_b32 v9, v9, 32, v71
	v_mul_u32_u24_e32 v9, 0x48, v9
	v_lshl_add_u32 v139, v9, 1, v8
	v_mov_b32_e32 v8, 0
	ds_write_b128 v137, v[48:51] offset:36864
	ds_write_b128 v137, v[56:59] offset:41472
	s_mov_b32 s25, 0
	s_movk_i32 s24, 0xc0
	v_mov_b32_e32 v9, v8
	v_mov_b32_e32 v10, v8
	v_mov_b32_e32 v11, v8
	v_mov_b32_e32 v16, v8
	v_mov_b32_e32 v17, v8
	v_mov_b32_e32 v18, v8
	v_mov_b32_e32 v19, v8
	v_mov_b32_e32 v28, v8
	v_mov_b32_e32 v29, v8
	v_mov_b32_e32 v30, v8
	v_mov_b32_e32 v31, v8
	v_mov_b32_e32 v40, v8
	v_mov_b32_e32 v41, v8
	v_mov_b32_e32 v42, v8
	v_mov_b32_e32 v43, v8
	v_mov_b32_e32 v48, v8
	v_mov_b32_e32 v49, v8
	v_mov_b32_e32 v50, v8
	v_mov_b32_e32 v51, v8
	v_mov_b32_e32 v56, v8
	v_mov_b32_e32 v57, v8
	v_mov_b32_e32 v58, v8
	v_mov_b32_e32 v59, v8
	v_mov_b32_e32 v60, v8
	v_mov_b32_e32 v61, v8
	v_mov_b32_e32 v62, v8
	v_mov_b32_e32 v63, v8
	v_mov_b32_e32 v68, v8
	v_mov_b32_e32 v69, v8
	v_mov_b32_e32 v70, v8
	v_mov_b32_e32 v71, v8
	s_waitcnt lgkmcnt(0)
	s_barrier

; template <int BN, bool SWAP> ...
;     ...
;   const bfu* Apn = chain ? (An + (size_t)lrow * ldan + lch) : Ap;
;   const bfu* Bpn = chain ? (Bn + (size_t)lrow * ldbn + lch) : Bp;
;   auto gl = [&](bf16x8 (&ra)[4], bf16x8 (&rb)[NJ], int kt) {
;     const bool nx = (kt >= nk);
;     const bfu* pa = nx ? (chain ? Apn + (kt - nk) * 64 : Ap + (nk - 1) * 64) : Ap + kt * 64;
;     const bfu* pb = nx ? (chain ? Bpn + (kt - nk) * 64 : Bp + (nk - 1) * 64) : Bp + kt * 64;
;     const size_t sa = (nx && chain) ? (size_t)ldan : (size_t)lda, sb = (nx && chain) ? (size_t)ldbn : (size_t)ldb;
; #pragma unroll
;     for (int q = 0; q < 4; ++q) ra[q] = gld16(pa + (size_t)(32 * q) * sa);
; #pragma unroll
;     for (int q = 0; q < NJ; ++q) rb[q] = gld16(pb + (size_t)(32 * q) * sb);
;   };
;   auto wt = [&](bf16x8 (&ra)[4], bf16x8 (&rb)[NJ]) {
;     if (NJ == 4) asm volatile("s_waitcnt vmcnt(8)" : "+v"(ra[0]), "+v"(ra[1]), "+v"(ra[2]), "+v"(ra[3]), "+v"(rb[0]), "+v"(rb[1]), "+v"(rb[NJ - 2]), "+v"(rb[NJ - 1]) : : "memory");
;     else asm volatile("s_waitcnt vmcnt(6)" : "+v"(ra[0]), "+v"(ra[1]), "+v"(ra[2]), "+v"(ra[3]), "+v"(rb[0]), "+v"(rb[1]) : : "memory");
;   };
;   auto st = [&](const bf16x8 (&ra)[4], const bf16x8 (&rb)[NJ], int buf) {
; #pragma unroll
;     for (int q = 0; q < 4; ++q) *(bf16x8*)(As + (buf * 128 + lrow + 32 * q) * 72 + lch) = ra[q];
; #pragma unroll
;     for (int q = 0; q < NJ; ++q) *(bf16x8*)(Bs + (buf * BN + brow + ((SWAP && NJ == 4) ? (8 * (q & 1) + 64 * (q >> 1)) : 32 * q)) * 72 + lch) = rb[q];
;   };
;   auto comp = [&](int buf, auto&& mid) {
;     const bfu* as = As + buf * 128 * 72 + (wr * 64 + c15) * 72 + g * 8;
;     const bfu* bs = Bs + buf * BN * 72 + (wc * (BN / 2) + c15) * 72 + g * 8;
;     {
;       bf16x8 a0[4], b0[NJ];
; #pragma unroll
;       for (int i = 0; i < 4; ++i) a0[i] = *(const bf16x8*)(as + i * 16 * 72);
; #pragma unroll
;       for (int j = 0; j < NJ; ++j) b0[j] = *(const bf16x8*)(bs + j * 16 * 72);
;       mid();
;       __builtin_amdgcn_s_setprio(1);
; #pragma unroll
;       for (int i = 0; i < 4; ++i)
; #pragma unroll
;         for (int j = 0; j < NJ; ++j) acc[i][j] = SWAP ? MFMA16(b0[j], a0[i], acc[i][j]) : MFMA16(a0[i], b0[j], acc[i][j]);
;       __builtin_amdgcn_s_setprio(0);
;     }
;     {
;       bf16x8 a1[4], b1[NJ];
; #pragma unroll
;       for (int i = 0; i < 4; ++i) a1[i] = *(const bf16x8*)(as + i * 16 * 72 + 32);
.LBB0_502:
	v_mov_b32_e32 v75, v174
	s_mov_b64 s[10:11], 0xc000
	v_ashrrev_i32_e32 v4, 3, v75
	v_ashrrev_i32_e32 v5, 31, v4
	v_lshlrev_b64 v[6:7], 9, v[4:5]
	v_lshlrev_b32_e32 v14, 4, v75
	v_lshl_add_u64 v[12:13], s[16:17], 0, v[6:7]
	v_and_b32_e32 v152, 0x70, v14
	v_lshl_add_u64 v[6:7], s[18:19], 0, v[6:7]
	v_lshl_add_u64 v[150:151], v[6:7], 0, v[152:153]
	v_lshlrev_b32_e32 v6, 2, v4
	v_lshrrev_b32_e32 v7, 1, v4
	v_lshl_add_u64 v[148:149], v[12:13], 0, v[152:153]
	v_and_b32_e32 v6, 16, v6
	v_and_b32_e32 v7, 12, v7
	v_and_b32_e32 v12, 3, v4
	v_or3_b32 v87, v12, v7, v6
	v_lshlrev_b64 v[6:7], 11, v[4:5]
	v_lshl_add_u64 v[12:13], s[20:21], 0, v[6:7]
	v_lshl_add_u64 v[164:165], v[12:13], 0, v[152:153]
	v_lshl_add_u64 v[6:7], s[22:23], 0, v[6:7]
	global_load_dwordx4 v[12:15], v[148:149], off
	s_mov_b64 s[16:17], 0x4000
	v_lshl_add_u64 v[166:167], v[6:7], 0, v[152:153]
	v_lshl_add_u64 v[6:7], v[148:149], 0, s[16:17]
	global_load_dwordx4 v[16:19], v[6:7], off
	v_lshl_add_u64 v[6:7], v[148:149], 0, s[34:35]
	global_load_dwordx4 v[20:23], v[6:7], off
	v_lshl_add_u64 v[6:7], v[148:149], 0, s[10:11]
	global_load_dwordx4 v[24:27], v[6:7], off
	global_load_dwordx4 v[36:39], v[150:151], off
	v_lshl_add_u64 v[6:7], v[150:151], 0, s[16:17]
	global_load_dwordx4 v[40:43], v[6:7], off
	v_lshl_add_u64 v[52:53], v[148:149], 0, s[80:81]
	s_mov_b64 s[16:17], 0x4080
	global_load_dwordx4 v[52:55], v[52:53], off
	v_lshl_add_u64 v[56:57], v[148:149], 0, s[16:17]
	s_mov_b64 s[10:11], 0x8080
	global_load_dwordx4 v[56:59], v[56:57], off
	v_lshl_add_u64 v[68:69], v[148:149], 0, s[10:11]
	s_mov_b64 s[10:11], 0xc080
	global_load_dwordx4 v[68:71], v[68:69], off
	v_lshl_add_u64 v[78:79], v[148:149], 0, s[10:11]
	global_load_dwordx4 v[78:81], v[78:79], off
	v_lshl_add_u64 v[6:7], v[150:151], 0, s[80:81]
	global_load_dwordx4 v[82:85], v[6:7], off
	v_lshl_add_u64 v[6:7], v[150:151], 0, s[16:17]
	global_load_dwordx4 v[88:91], v[6:7], off
	s_barrier
	s_waitcnt vmcnt(6)
	v_add_u32_e32 v92, 4, v4
	v_and_b32_e32 v92, 8, v92
	v_lshlrev_b32_e32 v92, 1, v92
	v_xor_b32_e32 v92, v152, v92
	v_mad_u32_u24 v6, v4, s89, v92
	v_and_b32_e32 v77, 15, v75
	ds_write_b128 v6, v[12:15]
	ds_write_b128 v6, v[16:19] offset:4608
	ds_write_b128 v6, v[20:23] offset:9216
	ds_write_b128 v6, v[24:27] offset:13824
	v_lshrrev_b32_e32 v13, 1, v75
	v_and_or_b32 v4, v13, s74, v77
	v_and_b32_e32 v12, 48, v75
	v_add_u32_e32 v92, 4, v75
	v_and_b32_e32 v92, 8, v92
	v_lshlrev_b32_e32 v92, 1, v92
	v_xor_b32_e32 v12, v12, v92
	v_mad_u32_u24 v4, v4, s89, v12
	v_and_or_b32 v5, v13, 32, v77
	v_mul_u32_u24_e32 v5, 0x48, v5
	s_mov_b64 s[10:11], 0x100
	v_add_u32_e32 v92, 4, v87
	v_and_b32_e32 v92, 8, v92
	v_lshlrev_b32_e32 v92, 1, v92
	v_xor_b32_e32 v92, v152, v92
	v_mad_u32_u24 v7, v87, s89, v92
	v_lshl_add_u32 v75, v5, 1, v12
	v_lshl_add_u64 v[12:13], v[148:149], 0, s[10:11]
	s_mov_b64 s[16:17], 0x4100
	ds_write_b128 v7, v[36:39] offset:36864
	ds_write_b128 v7, v[40:43] offset:41472
	s_waitcnt lgkmcnt(0)
	s_barrier
	v_lshl_add_u64 v[36:37], v[150:151], 0, s[10:11]
	global_load_dwordx4 v[12:15], v[12:13], off
	v_lshl_add_u64 v[16:17], v[148:149], 0, s[16:17]
	s_mov_b64 s[10:11], 0x8100
	global_load_dwordx4 v[16:19], v[16:17], off
	v_lshl_add_u64 v[20:21], v[148:149], 0, s[10:11]
	s_mov_b64 s[10:11], 0xc100
	global_load_dwordx4 v[20:23], v[20:21], off
	v_lshl_add_u64 v[24:25], v[148:149], 0, s[10:11]
	global_load_dwordx4 v[24:27], v[24:25], off
	global_load_dwordx4 v[36:39], v[36:37], off
	v_lshl_add_u64 v[40:41], v[150:151], 0, s[16:17]
	global_load_dwordx4 v[40:43], v[40:41], off
	ds_read_b128 v[92:95], v4
	ds_read_b128 v[96:99], v4 offset:2304
	ds_read_b128 v[100:103], v4 offset:4608
	ds_read_b128 v[104:107], v4 offset:6912
	ds_read_b128 v[108:111], v75 offset:36864
	ds_read_b128 v[112:115], v75 offset:39168
	s_waitcnt vmcnt(6)
	s_cmp_eq_u64 s[20:21], 0
	s_cselect_b64 vcc, -1, 0
	ds_write_b128 v6, v[52:55] offset:18432
	ds_write_b128 v6, v[56:59] offset:23040
	ds_write_b128 v6, v[68:71] offset:27648
	ds_write_b128 v6, v[78:81] offset:32256
	ds_write_b128 v7, v[82:85] offset:46080
	ds_write_b128 v7, v[88:91] offset:50688
	s_setprio 1
	s_waitcnt lgkmcnt(7)
	v_mfma_f32_16x16x32_bf16 v[52:55], v[108:111], v[92:95], 0
	s_waitcnt lgkmcnt(6)
	v_mfma_f32_16x16x32_bf16 v[56:59], v[112:115], v[92:95], 0
	v_mfma_f32_16x16x32_bf16 v[68:71], v[108:111], v[96:99], 0
	v_mfma_f32_16x16x32_bf16 v[78:81], v[112:115], v[96:99], 0
	v_mfma_f32_16x16x32_bf16 v[82:85], v[108:111], v[100:103], 0
	v_mfma_f32_16x16x32_bf16 v[88:91], v[112:115], v[100:103], 0
	v_mfma_f32_16x16x32_bf16 v[92:95], v[108:111], v[104:107], 0
	v_mfma_f32_16x16x32_bf16 v[96:99], v[112:115], v[104:107], 0
	s_setprio 0
	ds_read_b128 v[100:103], v4 offset:64
	ds_read_b128 v[104:107], v4 offset:2368
	ds_read_b128 v[108:111], v4 offset:4672
	ds_read_b128 v[112:115], v4 offset:6976
	ds_read_b128 v[116:119], v75 offset:36928
	ds_read_b128 v[120:123], v75 offset:39232
	s_setprio 1
	s_waitcnt lgkmcnt(1)
	v_mfma_f32_16x16x32_bf16 v[52:55], v[116:119], v[100:103], v[52:55]
	s_waitcnt lgkmcnt(0)
	v_mfma_f32_16x16x32_bf16 v[56:59], v[120:123], v[100:103], v[56:59]
	v_mfma_f32_16x16x32_bf16 v[68:71], v[116:119], v[104:107], v[68:71]
	v_mfma_f32_16x16x32_bf16 v[78:81], v[120:123], v[104:107], v[78:81]
	v_mfma_f32_16x16x32_bf16 v[82:85], v[116:119], v[108:111], v[82:85]
	v_mfma_f32_16x16x32_bf16 v[88:91], v[120:123], v[108:111], v[88:91]
	v_mfma_f32_16x16x32_bf16 v[92:95], v[116:119], v[112:115], v[92:95]
	v_mfma_f32_16x16x32_bf16 v[96:99], v[120:123], v[112:115], v[96:99]
	s_setprio 0
	s_mov_b64 s[10:11], 0x180
	v_lshl_add_u64 v[100:101], v[148:149], 0, s[10:11]
	s_mov_b64 s[16:17], 0x4180
	s_barrier
; template <int BN, bool SWAP> ...
;     ...
;     const bfu* pa = nx ? (chain ? Apn + (kt - nk) * 64 : Ap + (nk - 1) * 64) : Ap + kt * 64;
;     const bfu* pb = nx ? (chain ? Bpn + (kt - nk) * 64 : Bp + (nk - 1) * 64) : Bp + kt * 64;
;     const size_t sa = (nx && chain) ? (size_t)ldan : (size_t)lda, sb = (nx && chain) ? (size_t)ldbn : (size_t)ldb;
; #pragma unroll
;     for (int q = 0; q < 4; ++q) ra[q] = gld16(pa + (size_t)(32 * q) * sa);
; #pragma unroll
;     for (int q = 0; q < NJ; ++q) rb[q] = gld16(pb + (size_t)(32 * q) * sb);
;   };
;   auto wt = [&](bf16x8 (&ra)[4], bf16x8 (&rb)[NJ]) {
;     if (NJ == 4) asm volatile("s_waitcnt vmcnt(8)" : "+v"(ra[0]), "+v"(ra[1]), "+v"(ra[2]), "+v"(ra[3]), "+v"(rb[0]), "+v"(rb[1]), "+v"(rb[NJ - 2]), "+v"(rb[NJ - 1]) : : "memory");
;     else asm volatile("s_waitcnt vmcnt(6)" : "+v"(ra[0]), "+v"(ra[1]), "+v"(ra[2]), "+v"(ra[3]), "+v"(rb[0]), "+v"(rb[1]) : : "memory");
;   };
;   auto st = [&](const bf16x8 (&ra)[4], const bf16x8 (&rb)[NJ], int buf) {
; #pragma unroll
;     for (int q = 0; q < 4; ++q) *(bf16x8*)(As + (buf * 128 + lrow + 32 * q) * 72 + lch) = ra[q];
; #pragma unroll
;     for (int q = 0; q < NJ; ++q) *(bf16x8*)(Bs + (buf * BN + brow + ((SWAP && NJ == 4) ? (8 * (q & 1) + 64 * (q >> 1)) : 32 * q)) * 72 + lch) = rb[q];
;   };
;   auto comp = [&](int buf, auto&& mid) {
;     const bfu* as = As + buf * 128 * 72 + (wr * 64 + c15) * 72 + g * 8;
;     const bfu* bs = Bs + buf * BN * 72 + (wc * (BN / 2) + c15) * 72 + g * 8;
;     {
;       bf16x8 a0[4], b0[NJ];
; #pragma unroll
;       for (int i = 0; i < 4; ++i) a0[i] = *(const bf16x8*)(as + i * 16 * 72);
; #pragma unroll
;       for (int j = 0; j < NJ; ++j) b0[j] = *(const bf16x8*)(bs + j * 16 * 72);
;       mid();
;       __builtin_amdgcn_s_setprio(1);
; #pragma unroll
;       for (int i = 0; i < 4; ++i)
; #pragma unroll
;         for (int j = 0; j < NJ; ++j) acc[i][j] = SWAP ? MFMA16(b0[j], a0[i], acc[i][j]) : MFMA16(a0[i], b0[j], acc[i][j]);
;       __builtin_amdgcn_s_setprio(0);
;     }
;     {
;       bf16x8 a1[4], b1[NJ];
; #pragma unroll
;       for (int i = 0; i < 4; ++i) a1[i] = *(const bf16x8*)(as + i * 16 * 72 + 32);
; #pragma unroll
;       for (int j = 0; j < NJ; ++j) b1[j] = *(const bf16x8*)(bs + j * 16 * 72 + 32);
;       __builtin_amdgcn_s_setprio(1);
; #pragma unroll
;       for (int i = 0; i < 4; ++i)
; #pragma unroll
	v_lshl_add_u64 v[116:117], v[150:151], 0, s[10:11]
	global_load_dwordx4 v[100:103], v[100:101], off
	v_lshl_add_u64 v[104:105], v[148:149], 0, s[16:17]
	s_mov_b64 s[10:11], 0x8180
	global_load_dwordx4 v[104:107], v[104:105], off
	v_lshl_add_u64 v[108:109], v[148:149], 0, s[10:11]
	s_mov_b64 s[10:11], 0xc180
	global_load_dwordx4 v[108:111], v[108:109], off
	v_lshl_add_u64 v[112:113], v[148:149], 0, s[10:11]
	global_load_dwordx4 v[112:115], v[112:113], off
	global_load_dwordx4 v[116:119], v[116:117], off
	v_lshl_add_u64 v[120:121], v[150:151], 0, s[16:17]
	global_load_dwordx4 v[120:123], v[120:121], off
	ds_read_b128 v[124:127], v4 offset:18432
	ds_read_b128 v[128:131], v4 offset:20736
	ds_read_b128 v[132:135], v4 offset:23040
	ds_read_b128 v[136:139], v4 offset:25344
	ds_read_b128 v[140:143], v75 offset:46080
	ds_read_b128 v[144:147], v75 offset:48384
	s_waitcnt vmcnt(6)
	ds_write_b128 v6, v[12:15]
	ds_write_b128 v6, v[16:19] offset:4608
	ds_write_b128 v6, v[20:23] offset:9216
	ds_write_b128 v6, v[24:27] offset:13824
	ds_write_b128 v7, v[36:39] offset:36864
	ds_write_b128 v7, v[40:43] offset:41472
	s_setprio 1
	s_waitcnt lgkmcnt(7)
	v_mfma_f32_16x16x32_bf16 v[12:15], v[140:143], v[124:127], v[52:55]
	s_waitcnt lgkmcnt(6)
	v_mfma_f32_16x16x32_bf16 v[16:19], v[144:147], v[124:127], v[56:59]
	v_mfma_f32_16x16x32_bf16 v[20:23], v[140:143], v[128:131], v[68:71]
	v_mfma_f32_16x16x32_bf16 v[24:27], v[144:147], v[128:131], v[78:81]
	v_mfma_f32_16x16x32_bf16 v[36:39], v[140:143], v[132:135], v[82:85]
	v_mfma_f32_16x16x32_bf16 v[40:43], v[144:147], v[132:135], v[88:91]
	v_mfma_f32_16x16x32_bf16 v[52:55], v[140:143], v[136:139], v[92:95]
	v_mfma_f32_16x16x32_bf16 v[56:59], v[144:147], v[136:139], v[96:99]
	s_setprio 0
	ds_read_b128 v[68:71], v4 offset:18496
	ds_read_b128 v[78:81], v4 offset:20800
	ds_read_b128 v[82:85], v4 offset:23104
	ds_read_b128 v[88:91], v4 offset:25408
	ds_read_b128 v[92:95], v75 offset:46144
	ds_read_b128 v[96:99], v75 offset:48448
	s_setprio 1
	s_waitcnt lgkmcnt(1)
	v_mfma_f32_16x16x32_bf16 v[12:15], v[92:95], v[68:71], v[12:15]
	s_waitcnt lgkmcnt(0)
	v_mfma_f32_16x16x32_bf16 v[16:19], v[96:99], v[68:71], v[16:19]
	v_mfma_f32_16x16x32_bf16 v[20:23], v[92:95], v[78:81], v[20:23]
	v_mfma_f32_16x16x32_bf16 v[24:27], v[96:99], v[78:81], v[24:27]
	v_mfma_f32_16x16x32_bf16 v[36:39], v[92:95], v[82:85], v[36:39]
	v_mfma_f32_16x16x32_bf16 v[40:43], v[96:99], v[82:85], v[40:43]
	v_mfma_f32_16x16x32_bf16 v[52:55], v[92:95], v[88:91], v[52:55]
	v_mfma_f32_16x16x32_bf16 v[56:59], v[96:99], v[88:91], v[56:59]
	s_setprio 0
	s_and_b64 s[10:11], vcc, exec
	s_cselect_b32 s2, 0x180, 0
	v_cndmask_b32_e32 v149, v165, v149, vcc
	v_cndmask_b32_e32 v148, v164, v148, vcc
	v_cndmask_b32_e32 v151, v167, v151, vcc
	v_cndmask_b32_e32 v150, v166, v150, vcc
	s_cselect_b32 s11, 0x100, s33
	v_lshl_add_u64 v[96:97], v[150:151], 0, s[2:3]
	v_lshl_add_u64 v[88:89], v[148:149], 0, s[2:3]
	s_movk_i32 s2, 0x180
	s_cselect_b32 s10, 0xc000, s75
	s_cselect_b32 s16, s2, 0x80
	s_lshl_b32 s2, s11, 6
	s_barrier
	global_load_dwordx4 v[68:71], v[88:89], off
	v_lshl_add_u64 v[78:79], v[88:89], 0, s[2:3]
	s_lshl_b32 s18, s11, 7
	s_mov_b32 s19, s3
	global_load_dwordx4 v[78:81], v[78:79], off
	v_lshl_add_u64 v[82:83], v[88:89], 0, s[18:19]
	s_mov_b32 s11, s3
	global_load_dwordx4 v[82:85], v[82:83], off
	v_lshl_add_u64 v[88:89], v[88:89], 0, s[10:11]
	global_load_dwordx4 v[88:91], v[88:89], off
	global_load_dwordx4 v[92:95], v[96:97], off
	v_lshl_add_u64 v[96:97], v[96:97], 0, s[2:3]
	global_load_dwordx4 v[96:99], v[96:97], off
	ds_read_b128 v[124:127], v4
	ds_read_b128 v[128:131], v4 offset:2304
	ds_read_b128 v[132:135], v4 offset:4608
	ds_read_b128 v[136:139], v4 offset:6912
	ds_read_b128 v[140:143], v75 offset:36864
	ds_read_b128 v[144:147], v75 offset:39168
	s_waitcnt vmcnt(6)
	ds_write_b128 v6, v[100:103] offset:18432
	ds_write_b128 v6, v[104:107] offset:23040
	ds_write_b128 v6, v[108:111] offset:27648
	ds_write_b128 v6, v[112:115] offset:32256
	ds_write_b128 v7, v[116:119] offset:46080
	ds_write_b128 v7, v[120:123] offset:50688
	s_setprio 1
	s_waitcnt lgkmcnt(7)
	v_mfma_f32_16x16x32_bf16 v[12:15], v[140:143], v[124:127], v[12:15]
	s_waitcnt lgkmcnt(6)
	v_mfma_f32_16x16x32_bf16 v[16:19], v[144:147], v[124:127], v[16:19]
	v_mfma_f32_16x16x32_bf16 v[20:23], v[140:143], v[128:131], v[20:23]
	v_mfma_f32_16x16x32_bf16 v[24:27], v[144:147], v[128:131], v[24:27]
	v_mfma_f32_16x16x32_bf16 v[36:39], v[140:143], v[132:135], v[36:39]
	v_mfma_f32_16x16x32_bf16 v[40:43], v[144:147], v[132:135], v[40:43]
	v_mfma_f32_16x16x32_bf16 v[52:55], v[140:143], v[136:139], v[52:55]
	v_mfma_f32_16x16x32_bf16 v[56:59], v[144:147], v[136:139], v[56:59]
	s_setprio 0
	ds_read_b128 v[100:103], v4 offset:64
	ds_read_b128 v[104:107], v4 offset:2368
	ds_read_b128 v[108:111], v4 offset:4672
	ds_read_b128 v[112:115], v4 offset:6976
	ds_read_b128 v[116:119], v75 offset:36928
	ds_read_b128 v[120:123], v75 offset:39232
	s_setprio 1
	s_waitcnt lgkmcnt(1)
	v_mfma_f32_16x16x32_bf16 v[12:15], v[116:119], v[100:103], v[12:15]
	s_waitcnt lgkmcnt(0)
	v_mfma_f32_16x16x32_bf16 v[16:19], v[120:123], v[100:103], v[16:19]
	v_mfma_f32_16x16x32_bf16 v[20:23], v[116:119], v[104:107], v[20:23]
	v_mfma_f32_16x16x32_bf16 v[24:27], v[120:123], v[104:107], v[24:27]
	v_mfma_f32_16x16x32_bf16 v[36:39], v[116:119], v[108:111], v[36:39]
	v_mfma_f32_16x16x32_bf16 v[40:43], v[120:123], v[108:111], v[40:43]
	v_mfma_f32_16x16x32_bf16 v[52:55], v[116:119], v[112:115], v[52:55]
	v_mfma_f32_16x16x32_bf16 v[56:59], v[120:123], v[112:115], v[56:59]
	s_setprio 0
	s_mov_b32 s17, s3
	v_lshl_add_u64 v[112:113], v[148:149], 0, s[16:17]
	s_barrier
; #define MFMA16(a, b, c) __builtin_amdgcn_mfma_f32_16x16x32_bf16((a), (b), (c), 0, 0, 0)
;   __device__ __forceinline__ float* gl() const { return (float*)(b + L::o_gl); }
;   __device__ __forceinline__ float* r() const { return (float*)(b + L::o_r); }
; template <int BN, bool SWAP> ...
;     ...
;         for (int j = 0; j < NJ; ++j) acc[i][j] = SWAP ? MFMA16(b0[j], a0[i], acc[i][j]) : MFMA16(a0[i], b0[j], acc[i][j]);
;       __builtin_amdgcn_s_setprio(0);
;     }
;     {
;       bf16x8 a1[4], b1[NJ];
; #pragma unroll
;       for (int i = 0; i < 4; ++i) a1[i] = *(const bf16x8*)(as + i * 16 * 72 + 32);
; #pragma unroll
;       for (int j = 0; j < NJ; ++j) b1[j] = *(const bf16x8*)(bs + j * 16 * 72 + 32);
;       __builtin_amdgcn_s_setprio(1);
; #pragma unroll
;       for (int i = 0; i < 4; ++i)
; #pragma unroll
;         for (int j = 0; j < NJ; ++j) acc[i][j] = SWAP ? MFMA16(b1[j], a1[i], acc[i][j]) : MFMA16(a1[i], b1[j], acc[i][j]);
;       __builtin_amdgcn_s_setprio(0);
;     }
;   };
;   gl(ra0, rb0, 0);
;   gl(ra1, rb1, 1);
;   __syncthreads();
;   wt(ra0, rb0);
;   st(ra0, rb0, 0);
;   __syncthreads();
;   for (int kt = 0; kt < nk; kt += 2) {
;     gl(ra0, rb0, kt + 2);
;     comp(0, [&]() { wt(ra1, rb1); st(ra1, rb1, 1); });
;     __syncthreads();
;     gl(ra1, rb1, kt + 3);
;     comp(1, [&]() { wt(ra0, rb0); st(ra0, rb0, 0); });
;     __syncthreads();
;   }
;   if (NJ == 4) asm volatile("s_waitcnt vmcnt(0)" : "+v"(ra1[0]), "+v"(ra1[1]), "+v"(ra1[2]), "+v"(ra1[3]), "+v"(rb1[0]), "+v"(rb1[1]), "+v"(rb1[NJ - 2]), "+v"(rb1[NJ - 1]) : : "memory");
; template <int G>
; __device__ __forceinline__ void p6(const Params& P, const Ptrs<G>& w, int pass, int layer, bfu* sm, const XcdInfo& xi) {
;     ...
;     const float* bgp = P.b_ple_gate + layer * 1024 + n0 + wc * 32 + 8 * g;
;     const float4 bg0 = *(const float4*)bgp, bg1 = *(const float4*)(bgp + 4);
;     float* rp = w.r() + (size_t)(m0 + wr * 64 + c15) * 1024 + n0 + wc * 32 + 8 * g;
; #pragma unroll
;     for (int i = 0; i < 4; ++i) {
;       float* rq = rp + (size_t)(16 * i) * 1024;
;       float4 v0 = *(const float4*)rq, v1 = *(const float4*)(rq + 4);
	global_load_dwordx4 v[100:103], v[112:113], off
	v_lshl_add_u64 v[104:105], v[112:113], 0, s[2:3]
	global_load_dwordx4 v[104:107], v[104:105], off
	v_lshl_add_u64 v[108:109], v[112:113], 0, s[18:19]
	global_load_dwordx4 v[108:111], v[108:109], off
	v_lshl_add_u64 v[112:113], v[112:113], 0, s[10:11]
	v_lshl_add_u64 v[120:121], v[150:151], 0, s[16:17]
	global_load_dwordx4 v[112:115], v[112:113], off
	global_load_dwordx4 v[116:119], v[120:121], off
	v_lshl_add_u64 v[120:121], v[120:121], 0, s[2:3]
	global_load_dwordx4 v[120:123], v[120:121], off
	ds_read_b128 v[124:127], v4 offset:18432
	ds_read_b128 v[128:131], v4 offset:20736
	ds_read_b128 v[132:135], v4 offset:23040
	ds_read_b128 v[136:139], v4 offset:25344
	ds_read_b128 v[140:143], v75 offset:46080
	ds_read_b128 v[144:147], v75 offset:48384
	s_waitcnt vmcnt(6)
	ds_write_b128 v6, v[68:71]
	ds_write_b128 v6, v[78:81] offset:4608
	ds_write_b128 v6, v[82:85] offset:9216
	ds_write_b128 v6, v[88:91] offset:13824
	ds_write_b128 v7, v[92:95] offset:36864
	ds_write_b128 v7, v[96:99] offset:41472
	s_setprio 1
	s_waitcnt lgkmcnt(7)
	v_mfma_f32_16x16x32_bf16 v[12:15], v[140:143], v[124:127], v[12:15]
	s_waitcnt lgkmcnt(6)
	v_mfma_f32_16x16x32_bf16 v[16:19], v[144:147], v[124:127], v[16:19]
	v_mfma_f32_16x16x32_bf16 v[20:23], v[140:143], v[128:131], v[20:23]
	v_mfma_f32_16x16x32_bf16 v[24:27], v[144:147], v[128:131], v[24:27]
	v_mfma_f32_16x16x32_bf16 v[36:39], v[140:143], v[132:135], v[36:39]
	v_mfma_f32_16x16x32_bf16 v[78:81], v[144:147], v[132:135], v[40:43]
	v_mfma_f32_16x16x32_bf16 v[82:85], v[140:143], v[136:139], v[52:55]
	v_mfma_f32_16x16x32_bf16 v[88:91], v[144:147], v[136:139], v[56:59]
	s_setprio 0
	ds_read_b128 v[40:43], v4 offset:18496
	ds_read_b128 v[92:95], v4 offset:20800
	ds_read_b128 v[96:99], v4 offset:23104
	ds_read_b128 v[4:7], v4 offset:25408
	ds_read_b128 v[124:127], v75 offset:46144
	ds_read_b128 v[128:131], v75 offset:48448
	s_setprio 1
	s_waitcnt lgkmcnt(1)
	v_mfma_f32_16x16x32_bf16 v[68:71], v[124:127], v[40:43], v[12:15]
	s_waitcnt lgkmcnt(0)
	v_mfma_f32_16x16x32_bf16 v[56:59], v[128:131], v[40:43], v[16:19]
	v_mfma_f32_16x16x32_bf16 v[52:55], v[124:127], v[92:95], v[20:23]
	v_mfma_f32_16x16x32_bf16 v[40:43], v[128:131], v[92:95], v[24:27]
	v_mfma_f32_16x16x32_bf16 v[36:39], v[124:127], v[96:99], v[36:39]
	v_mfma_f32_16x16x32_bf16 v[20:23], v[128:131], v[96:99], v[78:81]
	v_mfma_f32_16x16x32_bf16 v[12:15], v[124:127], v[4:7], v[82:85]
	v_mfma_f32_16x16x32_bf16 v[4:7], v[128:131], v[4:7], v[88:91]
	s_setprio 0
	s_lshl_b64 s[10:11], s[14:15], 2
	s_barrier
	s_waitcnt vmcnt(0)
	v_lshl_add_u64 v[24:25], v[72:73], 0, s[10:11]
	global_load_dwordx4 v[16:19], v[24:25], off offset:16
	s_nop 0
	global_load_dwordx4 v[24:27], v[24:25], off
	v_add_u32_e32 v78, s12, v86
	v_ashrrev_i32_e32 v79, 31, v78
	v_lshlrev_b64 v[78:79], 12, v[78:79]
	v_lshl_add_u64 v[78:79], s[66:67], 0, v[78:79]
	v_lshl_add_u64 v[78:79], v[78:79], 0, s[10:11]
	v_mov_b32_e32 v75, v153
	v_lshl_add_u64 v[78:79], v[78:79], 0, v[74:75]
	v_mov_b32_e32 v77, v153
	v_lshl_add_u64 v[78:79], v[78:79], 0, v[76:77]
	s_waitcnt vmcnt(1)
	v_add_f32_e32 v60, v60, v16
	s_waitcnt vmcnt(0)
	v_add_f32_e32 v64, v64, v24
	v_mul_f32_e32 v64, 0xbfb8aa3b, v64
	v_mul_f32_e32 v60, 0xbfb8aa3b, v60
	v_exp_f32_e32 v88, v64
	v_add_f32_e32 v64, v65, v25
	v_exp_f32_e32 v82, v60
	v_add_f32_e32 v60, v61, v17
	v_mul_f32_e32 v64, 0xbfb8aa3b, v64
	v_mul_f32_e32 v60, 0xbfb8aa3b, v60
	v_exp_f32_e32 v89, v64
	v_add_f32_e32 v64, v66, v26
	v_exp_f32_e32 v83, v60
	v_add_f32_e32 v60, v62, v18
	v_mul_f32_e32 v64, 0xbfb8aa3b, v64
	v_mul_f32_e32 v60, 0xbfb8aa3b, v60
	v_exp_f32_e32 v84, v64
	v_add_f32_e32 v64, v67, v27
	v_exp_f32_e32 v80, v60
	v_add_f32_e32 v60, v63, v19
	v_mul_f32_e32 v64, 0xbfb8aa3b, v64
	v_mul_f32_e32 v60, 0xbfb8aa3b, v60
	v_exp_f32_e32 v85, v64
	v_exp_f32_e32 v81, v60
	global_load_dwordx4 v[60:63], v[78:79], off offset:16
	global_load_dwordx4 v[64:67], v[78:79], off
	v_pk_add_f32 v[88:89], v[88:89], 1.0 op_sel_hi:[1,0]
	s_nop 0
	v_div_scale_f32 v75, s[10:11], v89, v89, 1.0
	v_rcp_f32_e32 v77, v75
	s_nop 0
	v_fma_f32 v87, -v75, v77, 1.0
	v_fmac_f32_e32 v77, v87, v77
	v_div_scale_f32 v87, vcc, 1.0, v89, 1.0
	v_mul_f32_e32 v90, v87, v77
	v_fma_f32 v91, -v75, v90, v87
	v_fmac_f32_e32 v90, v91, v77
	v_fma_f32 v75, -v75, v90, v87
	v_div_fmas_f32 v75, v75, v77, v90
	v_div_fixup_f32 v89, v75, v89, 1.0
	v_div_scale_f32 v75, s[10:11], v88, v88, 1.0
	v_rcp_f32_e32 v77, v75
	s_nop 0
	v_fma_f32 v87, -v75, v77, 1.0
	v_fmac_f32_e32 v77, v87, v77
	v_div_scale_f32 v87, vcc, 1.0, v88, 1.0
	v_mul_f32_e32 v90, v87, v77
	v_fma_f32 v91, -v75, v90, v87
	v_fmac_f32_e32 v90, v91, v77
	v_fma_f32 v75, -v75, v90, v87
	v_div_fmas_f32 v75, v75, v77, v90
	v_div_fixup_f32 v88, v75, v88, 1.0
	s_waitcnt vmcnt(0)
; __device__ __forceinline__ float sigm(float x) { return 1.f / (1.f + __expf(-x)); }
; template <int G>
; __device__ __forceinline__ void p6(const Params& P, const Ptrs<G>& w, int pass, int layer, bfu* sm, const XcdInfo& xi) {
;     ...
;       float4 v0 = *(const float4*)rq, v1 = *(const float4*)(rq + 4);
;       v0.x += sigm(Ga[i][0][0] + bg0.x) * Pa[i][0][0]; v0.y += sigm(Ga[i][0][1] + bg0.y) * Pa[i][0][1];
;       v0.z += sigm(Ga[i][0][2] + bg0.z) * Pa[i][0][2]; v0.w += sigm(Ga[i][0][3] + bg0.w) * Pa[i][0][3];
;       v1.x += sigm(Ga[i][1][0] + bg1.x) * Pa[i][1][0]; v1.y += sigm(Ga[i][1][1] + bg1.y) * Pa[i][1][1];
;       v1.z += sigm(Ga[i][1][2] + bg1.z) * Pa[i][1][2]; v1.w += sigm(Ga[i][1][3] + bg1.w) * Pa[i][1][3];
;       *(float4*)rq = v0; *(float4*)(rq + 4) = v1;
	v_pk_fma_f32 v[64:65], v[68:69], v[88:89], v[64:65]
	v_pk_add_f32 v[68:69], v[84:85], 1.0 op_sel_hi:[1,0]
	s_nop 0
	v_div_scale_f32 v75, s[10:11], v69, v69, 1.0
	v_rcp_f32_e32 v77, v75
	s_nop 0
	v_fma_f32 v84, -v75, v77, 1.0
	v_fmac_f32_e32 v77, v84, v77
	v_div_scale_f32 v84, vcc, 1.0, v69, 1.0
	v_mul_f32_e32 v85, v84, v77
	v_fma_f32 v87, -v75, v85, v84
	v_fmac_f32_e32 v85, v87, v77
	v_fma_f32 v75, -v75, v85, v84
	v_div_fmas_f32 v75, v75, v77, v85
	v_div_fixup_f32 v69, v75, v69, 1.0
	v_div_scale_f32 v75, s[10:11], v68, v68, 1.0
	v_rcp_f32_e32 v77, v75
	s_nop 0
	v_fma_f32 v84, -v75, v77, 1.0
	v_fmac_f32_e32 v77, v84, v77
	v_div_scale_f32 v84, vcc, 1.0, v68, 1.0
	v_mul_f32_e32 v85, v84, v77
	v_fma_f32 v87, -v75, v85, v84
	v_fmac_f32_e32 v85, v87, v77
	v_fma_f32 v75, -v75, v85, v84
	v_div_fmas_f32 v75, v75, v77, v85
	v_div_fixup_f32 v68, v75, v68, 1.0
	v_pk_fma_f32 v[66:67], v[70:71], v[68:69], v[66:67]
	global_store_dwordx4 v[78:79], v[64:67], off
	s_nop 1
	v_pk_add_f32 v[64:65], v[82:83], 1.0 op_sel_hi:[1,0]
	s_nop 0
	v_div_scale_f32 v66, s[10:11], v65, v65, 1.0
	v_rcp_f32_e32 v67, v66
	s_nop 0
	v_fma_f32 v68, -v66, v67, 1.0
	v_fmac_f32_e32 v67, v68, v67
	v_div_scale_f32 v68, vcc, 1.0, v65, 1.0
	v_mul_f32_e32 v69, v68, v67
	v_fma_f32 v70, -v66, v69, v68
	v_fmac_f32_e32 v69, v70, v67
	v_fma_f32 v66, -v66, v69, v68
	v_div_fmas_f32 v66, v66, v67, v69
	v_div_fixup_f32 v65, v66, v65, 1.0
	v_div_scale_f32 v66, s[10:11], v64, v64, 1.0
	v_rcp_f32_e32 v67, v66
	s_nop 0
	v_fma_f32 v68, -v66, v67, 1.0
	v_fmac_f32_e32 v67, v68, v67
	v_div_scale_f32 v68, vcc, 1.0, v64, 1.0
	v_mul_f32_e32 v69, v68, v67
	v_fma_f32 v70, -v66, v69, v68
	v_fmac_f32_e32 v69, v70, v67
	v_fma_f32 v66, -v66, v69, v68
	v_div_fmas_f32 v66, v66, v67, v69
	v_div_fixup_f32 v64, v66, v64, 1.0
	v_pk_fma_f32 v[56:57], v[56:57], v[64:65], v[60:61]
	v_pk_add_f32 v[60:61], v[80:81], 1.0 op_sel_hi:[1,0]
	s_nop 0
	v_div_scale_f32 v64, s[10:11], v61, v61, 1.0
	v_rcp_f32_e32 v65, v64
	s_nop 0
	v_fma_f32 v66, -v64, v65, 1.0
	v_fmac_f32_e32 v65, v66, v65
	v_div_scale_f32 v66, vcc, 1.0, v61, 1.0
	v_mul_f32_e32 v67, v66, v65
	v_fma_f32 v68, -v64, v67, v66
	v_fmac_f32_e32 v67, v68, v65
	v_fma_f32 v64, -v64, v67, v66
	v_div_fmas_f32 v64, v64, v65, v67
	v_div_fixup_f32 v61, v64, v61, 1.0
	v_div_scale_f32 v64, s[10:11], v60, v60, 1.0
	v_rcp_f32_e32 v65, v64
	s_nop 0
	v_fma_f32 v66, -v64, v65, 1.0
	v_fmac_f32_e32 v65, v66, v65
	v_div_scale_f32 v66, vcc, 1.0, v60, 1.0
	v_mul_f32_e32 v67, v66, v65
	v_fma_f32 v68, -v64, v67, v66
	v_fmac_f32_e32 v67, v68, v65
	v_fma_f32 v64, -v64, v67, v66
	v_div_fmas_f32 v64, v64, v65, v67
	v_div_fixup_f32 v60, v64, v60, 1.0
	v_pk_fma_f32 v[58:59], v[58:59], v[60:61], v[62:63]
	global_store_dwordx4 v[78:79], v[56:59], off offset:16
	v_add_f32_e32 v48, v48, v24
	v_add_f32_e32 v44, v44, v16
	v_mul_f32_e32 v48, 0xbfb8aa3b, v48
	v_mul_f32_e32 v44, 0xbfb8aa3b, v44
	v_exp_f32_e32 v66, v48
	v_add_f32_e32 v48, v49, v25
	v_exp_f32_e32 v60, v44
	v_add_f32_e32 v44, v45, v17
	v_mul_f32_e32 v48, 0xbfb8aa3b, v48
	v_mul_f32_e32 v44, 0xbfb8aa3b, v44
	v_exp_f32_e32 v67, v48
	v_add_f32_e32 v48, v50, v26
	v_exp_f32_e32 v61, v44
	v_add_f32_e32 v44, v46, v18
	v_mul_f32_e32 v48, 0xbfb8aa3b, v48
	v_mul_f32_e32 v44, 0xbfb8aa3b, v44
	s_mov_b32 s2, 0x10000
	v_exp_f32_e32 v62, v48
	v_add_f32_e32 v48, v51, v27
	v_exp_f32_e32 v56, v44
	v_add_f32_e32 v44, v47, v19
	v_add_co_u32_e32 v58, vcc, s2, v78
	v_mul_f32_e32 v48, 0xbfb8aa3b, v48
	v_mul_f32_e32 v44, 0xbfb8aa3b, v44
	v_addc_co_u32_e32 v59, vcc, 0, v79, vcc
	v_lshl_add_u64 v[64:65], v[78:79], 0, s[76:77]
	v_exp_f32_e32 v63, v48
	v_exp_f32_e32 v57, v44
	global_load_dwordx4 v[48:51], v[58:59], off
	global_load_dwordx4 v[44:47], v[64:65], off offset:16
	v_pk_add_f32 v[64:65], v[66:67], 1.0 op_sel_hi:[1,0]
	s_nop 0
	v_div_scale_f32 v66, s[10:11], v65, v65, 1.0
	v_rcp_f32_e32 v67, v66
	s_nop 0
	v_fma_f32 v68, -v66, v67, 1.0
	v_fmac_f32_e32 v67, v68, v67
	v_div_scale_f32 v68, vcc, 1.0, v65, 1.0
	v_mul_f32_e32 v69, v68, v67
	v_fma_f32 v70, -v66, v69, v68
	v_fmac_f32_e32 v69, v70, v67
	v_fma_f32 v66, -v66, v69, v68
	v_div_fmas_f32 v66, v66, v67, v69
	v_div_fixup_f32 v65, v66, v65, 1.0
	v_div_scale_f32 v66, s[10:11], v64, v64, 1.0
	v_rcp_f32_e32 v67, v66
	s_nop 0
	v_fma_f32 v68, -v66, v67, 1.0
	v_fmac_f32_e32 v67, v68, v67
	v_div_scale_f32 v68, vcc, 1.0, v64, 1.0
	v_mul_f32_e32 v69, v68, v67
	v_fma_f32 v70, -v66, v69, v68
	v_fmac_f32_e32 v69, v70, v67
	v_fma_f32 v66, -v66, v69, v68
	v_div_fmas_f32 v66, v66, v67, v69
	v_div_fixup_f32 v64, v66, v64, 1.0
	s_waitcnt vmcnt(1)
	v_pk_fma_f32 v[48:49], v[52:53], v[64:65], v[48:49]
	v_pk_add_f32 v[52:53], v[62:63], 1.0 op_sel_hi:[1,0]
	s_nop 0
	v_div_scale_f32 v62, s[10:11], v53, v53, 1.0
	v_rcp_f32_e32 v63, v62
	s_nop 0
	v_fma_f32 v64, -v62, v63, 1.0
	v_fmac_f32_e32 v63, v64, v63
	v_div_scale_f32 v64, vcc, 1.0, v53, 1.0
	v_mul_f32_e32 v65, v64, v63
	v_fma_f32 v66, -v62, v65, v64
	v_fmac_f32_e32 v65, v66, v63
	v_fma_f32 v62, -v62, v65, v64
	v_div_fmas_f32 v62, v62, v63, v65
	v_div_fixup_f32 v53, v62, v53, 1.0
	v_div_scale_f32 v62, s[10:11], v52, v52, 1.0
	v_rcp_f32_e32 v63, v62
	s_nop 0
	v_fma_f32 v64, -v62, v63, 1.0
	v_fmac_f32_e32 v63, v64, v63
	v_div_scale_f32 v64, vcc, 1.0, v52, 1.0
	v_mul_f32_e32 v65, v64, v63
	v_fma_f32 v66, -v62, v65, v64
	v_fmac_f32_e32 v65, v66, v63
	v_fma_f32 v62, -v62, v65, v64
	v_div_fmas_f32 v62, v62, v63, v65
	v_div_fixup_f32 v52, v62, v52, 1.0
	v_pk_fma_f32 v[50:51], v[54:55], v[52:53], v[50:51]
	global_store_dwordx4 v[58:59], v[48:51], off
	s_nop 1
	v_pk_add_f32 v[48:49], v[60:61], 1.0 op_sel_hi:[1,0]
	s_nop 0
	v_div_scale_f32 v50, s[10:11], v49, v49, 1.0
	v_rcp_f32_e32 v51, v50
	s_nop 0
	v_fma_f32 v52, -v50, v51, 1.0
	v_fmac_f32_e32 v51, v52, v51
	v_div_scale_f32 v52, vcc, 1.0, v49, 1.0
	v_mul_f32_e32 v53, v52, v51
	v_fma_f32 v54, -v50, v53, v52
	v_fmac_f32_e32 v53, v54, v51
	v_fma_f32 v50, -v50, v53, v52
	v_div_fmas_f32 v50, v50, v51, v53
	v_div_fixup_f32 v49, v50, v49, 1.0
	v_div_scale_f32 v50, s[10:11], v48, v48, 1.0
	v_rcp_f32_e32 v51, v50
	s_nop 0
	v_fma_f32 v52, -v50, v51, 1.0
	v_fmac_f32_e32 v51, v52, v51
	v_div_scale_f32 v52, vcc, 1.0, v48, 1.0
	v_mul_f32_e32 v53, v52, v51
	v_fma_f32 v54, -v50, v53, v52
	v_fmac_f32_e32 v53, v54, v51
	v_fma_f32 v50, -v50, v53, v52
	v_div_fmas_f32 v50, v50, v51, v53
	v_div_fixup_f32 v48, v50, v48, 1.0
	s_waitcnt vmcnt(1)
; __device__ __forceinline__ float sigm(float x) { return 1.f / (1.f + __expf(-x)); }
; template <int G>
; __device__ __forceinline__ void p6(const Params& P, const Ptrs<G>& w, int pass, int layer, bfu* sm, const XcdInfo& xi) {
;     ...
;       float4 v0 = *(const float4*)rq, v1 = *(const float4*)(rq + 4);
;       v0.x += sigm(Ga[i][0][0] + bg0.x) * Pa[i][0][0]; v0.y += sigm(Ga[i][0][1] + bg0.y) * Pa[i][0][1];
;       v0.z += sigm(Ga[i][0][2] + bg0.z) * Pa[i][0][2]; v0.w += sigm(Ga[i][0][3] + bg0.w) * Pa[i][0][3];
;       v1.x += sigm(Ga[i][1][0] + bg1.x) * Pa[i][1][0]; v1.y += sigm(Ga[i][1][1] + bg1.y) * Pa[i][1][1];
;       v1.z += sigm(Ga[i][1][2] + bg1.z) * Pa[i][1][2]; v1.w += sigm(Ga[i][1][3] + bg1.w) * Pa[i][1][3];
;       *(float4*)rq = v0; *(float4*)(rq + 4) = v1;
	v_pk_fma_f32 v[40:41], v[40:41], v[48:49], v[44:45]
	v_pk_add_f32 v[44:45], v[56:57], 1.0 op_sel_hi:[1,0]
	s_nop 0
	v_div_scale_f32 v48, s[10:11], v45, v45, 1.0
	v_rcp_f32_e32 v49, v48
	s_nop 0
	v_fma_f32 v50, -v48, v49, 1.0
	v_fmac_f32_e32 v49, v50, v49
	v_div_scale_f32 v50, vcc, 1.0, v45, 1.0
	v_mul_f32_e32 v51, v50, v49
	v_fma_f32 v52, -v48, v51, v50
	v_fmac_f32_e32 v51, v52, v49
	v_fma_f32 v48, -v48, v51, v50
	v_div_fmas_f32 v48, v48, v49, v51
	v_div_fixup_f32 v45, v48, v45, 1.0
	v_div_scale_f32 v48, s[10:11], v44, v44, 1.0
	v_rcp_f32_e32 v49, v48
	s_nop 0
	v_fma_f32 v50, -v48, v49, 1.0
	v_fmac_f32_e32 v49, v50, v49
	v_div_scale_f32 v50, vcc, 1.0, v44, 1.0
	v_mul_f32_e32 v51, v50, v49
	v_fma_f32 v52, -v48, v51, v50
	v_fmac_f32_e32 v51, v52, v49
	v_fma_f32 v48, -v48, v51, v50
	v_div_fmas_f32 v48, v48, v49, v51
	v_div_fixup_f32 v44, v48, v44, 1.0
	v_pk_fma_f32 v[42:43], v[42:43], v[44:45], v[46:47]
	global_store_dwordx4 v[58:59], v[40:43], off offset:16
	v_add_f32_e32 v32, v32, v24
	v_add_f32_e32 v28, v28, v16
	v_mul_f32_e32 v32, 0xbfb8aa3b, v32
	v_mul_f32_e32 v28, 0xbfb8aa3b, v28
	v_exp_f32_e32 v50, v32
	v_add_f32_e32 v32, v33, v25
	v_exp_f32_e32 v44, v28
	v_add_f32_e32 v28, v29, v17
	v_mul_f32_e32 v32, 0xbfb8aa3b, v32
	v_mul_f32_e32 v28, 0xbfb8aa3b, v28
	v_exp_f32_e32 v51, v32
	v_add_f32_e32 v32, v34, v26
	v_exp_f32_e32 v45, v28
	v_add_f32_e32 v28, v30, v18
	v_mul_f32_e32 v32, 0xbfb8aa3b, v32
	v_mul_f32_e32 v28, 0xbfb8aa3b, v28
	v_exp_f32_e32 v46, v32
	v_add_f32_e32 v32, v35, v27
	v_exp_f32_e32 v40, v28
	v_add_f32_e32 v28, v31, v19
	v_add_co_u32_e32 v42, vcc, s7, v78
	v_mul_f32_e32 v32, 0xbfb8aa3b, v32
	v_mul_f32_e32 v28, 0xbfb8aa3b, v28
	v_addc_co_u32_e32 v43, vcc, 0, v79, vcc
	v_lshl_add_u64 v[48:49], v[78:79], 0, s[8:9]
	v_exp_f32_e32 v47, v32
	v_exp_f32_e32 v41, v28
	global_load_dwordx4 v[32:35], v[42:43], off
	global_load_dwordx4 v[28:31], v[48:49], off offset:16
	v_pk_add_f32 v[48:49], v[50:51], 1.0 op_sel_hi:[1,0]
	s_nop 0
	v_div_scale_f32 v50, s[10:11], v49, v49, 1.0
	v_rcp_f32_e32 v51, v50
	s_nop 0
	v_fma_f32 v52, -v50, v51, 1.0
	v_fmac_f32_e32 v51, v52, v51
	v_div_scale_f32 v52, vcc, 1.0, v49, 1.0
	v_mul_f32_e32 v53, v52, v51
	v_fma_f32 v54, -v50, v53, v52
	v_fmac_f32_e32 v53, v54, v51
	v_fma_f32 v50, -v50, v53, v52
	v_div_fmas_f32 v50, v50, v51, v53
	v_div_fixup_f32 v49, v50, v49, 1.0
	v_div_scale_f32 v50, s[10:11], v48, v48, 1.0
	v_rcp_f32_e32 v51, v50
	s_nop 0
	v_fma_f32 v52, -v50, v51, 1.0
	v_fmac_f32_e32 v51, v52, v51
	v_div_scale_f32 v52, vcc, 1.0, v48, 1.0
	v_mul_f32_e32 v53, v52, v51
	v_fma_f32 v54, -v50, v53, v52
	v_fmac_f32_e32 v53, v54, v51
	v_fma_f32 v50, -v50, v53, v52
	v_div_fmas_f32 v50, v50, v51, v53
	v_div_fixup_f32 v48, v50, v48, 1.0
	s_waitcnt vmcnt(1)
	v_pk_fma_f32 v[32:33], v[36:37], v[48:49], v[32:33]
	v_pk_add_f32 v[36:37], v[46:47], 1.0 op_sel_hi:[1,0]
	s_nop 0
	v_div_scale_f32 v46, s[10:11], v37, v37, 1.0
	v_rcp_f32_e32 v47, v46
	s_nop 0
	v_fma_f32 v48, -v46, v47, 1.0
	v_fmac_f32_e32 v47, v48, v47
	v_div_scale_f32 v48, vcc, 1.0, v37, 1.0
	v_mul_f32_e32 v49, v48, v47
	v_fma_f32 v50, -v46, v49, v48
	v_fmac_f32_e32 v49, v50, v47
	v_fma_f32 v46, -v46, v49, v48
	v_div_fmas_f32 v46, v46, v47, v49
	v_div_fixup_f32 v37, v46, v37, 1.0
	v_div_scale_f32 v46, s[10:11], v36, v36, 1.0
	v_rcp_f32_e32 v47, v46
	s_nop 0
	v_fma_f32 v48, -v46, v47, 1.0
	v_fmac_f32_e32 v47, v48, v47
	v_div_scale_f32 v48, vcc, 1.0, v36, 1.0
	v_mul_f32_e32 v49, v48, v47
	v_fma_f32 v50, -v46, v49, v48
	v_fmac_f32_e32 v49, v50, v47
	v_fma_f32 v46, -v46, v49, v48
	v_div_fmas_f32 v46, v46, v47, v49
	v_div_fixup_f32 v36, v46, v36, 1.0
	v_pk_fma_f32 v[34:35], v[38:39], v[36:37], v[34:35]
	global_store_dwordx4 v[42:43], v[32:35], off
	s_nop 1
	v_pk_add_f32 v[32:33], v[44:45], 1.0 op_sel_hi:[1,0]
	s_nop 0
	v_div_scale_f32 v34, s[10:11], v33, v33, 1.0
	v_rcp_f32_e32 v35, v34
	s_nop 0
	v_fma_f32 v36, -v34, v35, 1.0
	v_fmac_f32_e32 v35, v36, v35
	v_div_scale_f32 v36, vcc, 1.0, v33, 1.0
	v_mul_f32_e32 v37, v36, v35
	v_fma_f32 v38, -v34, v37, v36
	v_fmac_f32_e32 v37, v38, v35
	v_fma_f32 v34, -v34, v37, v36
	v_div_fmas_f32 v34, v34, v35, v37
	v_div_fixup_f32 v33, v34, v33, 1.0
	v_div_scale_f32 v34, s[10:11], v32, v32, 1.0
	v_rcp_f32_e32 v35, v34
	s_nop 0
	v_fma_f32 v36, -v34, v35, 1.0
	v_fmac_f32_e32 v35, v36, v35
	v_div_scale_f32 v36, vcc, 1.0, v32, 1.0
	v_mul_f32_e32 v37, v36, v35
	v_fma_f32 v38, -v34, v37, v36
	v_fmac_f32_e32 v37, v38, v35
	v_fma_f32 v34, -v34, v37, v36
	v_div_fmas_f32 v34, v34, v35, v37
	v_div_fixup_f32 v32, v34, v32, 1.0
	s_waitcnt vmcnt(1)
; __device__ __forceinline__ float sigm(float x) { return 1.f / (1.f + __expf(-x)); }
; template <int G>
; __device__ __forceinline__ void p6(const Params& P, const Ptrs<G>& w, int pass, int layer, bfu* sm, const XcdInfo& xi) {
;     ...
;       float4 v0 = *(const float4*)rq, v1 = *(const float4*)(rq + 4);
;       v0.x += sigm(Ga[i][0][0] + bg0.x) * Pa[i][0][0]; v0.y += sigm(Ga[i][0][1] + bg0.y) * Pa[i][0][1];
;       v0.z += sigm(Ga[i][0][2] + bg0.z) * Pa[i][0][2]; v0.w += sigm(Ga[i][0][3] + bg0.w) * Pa[i][0][3];
;       v1.x += sigm(Ga[i][1][0] + bg1.x) * Pa[i][1][0]; v1.y += sigm(Ga[i][1][1] + bg1.y) * Pa[i][1][1];
;       v1.z += sigm(Ga[i][1][2] + bg1.z) * Pa[i][1][2]; v1.w += sigm(Ga[i][1][3] + bg1.w) * Pa[i][1][3];
;       *(float4*)rq = v0; *(float4*)(rq + 4) = v1;
;       __builtin_amdgcn_sched_barrier(0);
;     }
;   }
	v_pk_fma_f32 v[20:21], v[20:21], v[32:33], v[28:29]
	v_pk_add_f32 v[28:29], v[40:41], 1.0 op_sel_hi:[1,0]
	s_nop 0
	v_div_scale_f32 v32, s[10:11], v29, v29, 1.0
	v_rcp_f32_e32 v33, v32
	s_nop 0
	v_fma_f32 v34, -v32, v33, 1.0
	v_fmac_f32_e32 v33, v34, v33
	v_div_scale_f32 v34, vcc, 1.0, v29, 1.0
	v_mul_f32_e32 v35, v34, v33
	v_fma_f32 v36, -v32, v35, v34
	v_fmac_f32_e32 v35, v36, v33
	v_fma_f32 v32, -v32, v35, v34
	v_div_fmas_f32 v32, v32, v33, v35
	v_div_fixup_f32 v29, v32, v29, 1.0
	v_div_scale_f32 v32, s[10:11], v28, v28, 1.0
	v_rcp_f32_e32 v33, v32
	s_nop 0
	v_fma_f32 v34, -v32, v33, 1.0
	v_fmac_f32_e32 v33, v34, v33
	v_div_scale_f32 v34, vcc, 1.0, v28, 1.0
	v_mul_f32_e32 v35, v34, v33
	v_fma_f32 v36, -v32, v35, v34
	v_fmac_f32_e32 v35, v36, v33
	v_fma_f32 v32, -v32, v35, v34
	v_div_fmas_f32 v32, v32, v33, v35
	v_div_fixup_f32 v28, v32, v28, 1.0
	v_pk_fma_f32 v[22:23], v[22:23], v[28:29], v[30:31]
	global_store_dwordx4 v[42:43], v[20:23], off offset:16
	v_add_f32_e32 v8, v8, v24
	v_add_f32_e32 v0, v0, v16
	v_mul_f32_e32 v8, 0xbfb8aa3b, v8
	v_mul_f32_e32 v0, 0xbfb8aa3b, v0
	v_exp_f32_e32 v24, v8
	v_add_f32_e32 v8, v9, v25
	v_exp_f32_e32 v20, v0
	v_add_f32_e32 v0, v1, v17
	v_mul_f32_e32 v8, 0xbfb8aa3b, v8
	v_mul_f32_e32 v0, 0xbfb8aa3b, v0
	v_exp_f32_e32 v25, v8
	v_add_f32_e32 v8, v10, v26
	v_exp_f32_e32 v21, v0
	v_add_f32_e32 v0, v2, v18
	v_mul_f32_e32 v8, 0xbfb8aa3b, v8
	v_mul_f32_e32 v0, 0xbfb8aa3b, v0
	v_exp_f32_e32 v22, v8
	v_add_f32_e32 v8, v11, v27
	v_exp_f32_e32 v16, v0
	v_add_f32_e32 v0, v3, v19
	v_add_co_u32_e32 v18, vcc, s75, v78
	v_mul_f32_e32 v8, 0xbfb8aa3b, v8
	v_mul_f32_e32 v0, 0xbfb8aa3b, v0
	v_addc_co_u32_e32 v19, vcc, 0, v79, vcc
	v_lshl_add_u64 v[28:29], v[78:79], 0, s[78:79]
	v_exp_f32_e32 v23, v8
	v_exp_f32_e32 v17, v0
	global_load_dwordx4 v[8:11], v[18:19], off
	global_load_dwordx4 v[0:3], v[28:29], off offset:16
	v_pk_add_f32 v[24:25], v[24:25], 1.0 op_sel_hi:[1,0]
	s_nop 0
	v_div_scale_f32 v26, s[10:11], v25, v25, 1.0
	v_rcp_f32_e32 v27, v26
	s_nop 0
	v_fma_f32 v28, -v26, v27, 1.0
	v_fmac_f32_e32 v27, v28, v27
	v_div_scale_f32 v28, vcc, 1.0, v25, 1.0
	v_mul_f32_e32 v29, v28, v27
	v_fma_f32 v30, -v26, v29, v28
	v_fmac_f32_e32 v29, v30, v27
	v_fma_f32 v26, -v26, v29, v28
	v_div_fmas_f32 v26, v26, v27, v29
	v_div_fixup_f32 v25, v26, v25, 1.0
	v_div_scale_f32 v26, s[10:11], v24, v24, 1.0
	v_rcp_f32_e32 v27, v26
	s_nop 0
	v_fma_f32 v28, -v26, v27, 1.0
	v_fmac_f32_e32 v27, v28, v27
	v_div_scale_f32 v28, vcc, 1.0, v24, 1.0
	v_mul_f32_e32 v29, v28, v27
	v_fma_f32 v30, -v26, v29, v28
	v_fmac_f32_e32 v29, v30, v27
	v_fma_f32 v26, -v26, v29, v28
	v_div_fmas_f32 v26, v26, v27, v29
	v_div_fixup_f32 v24, v26, v24, 1.0
	s_waitcnt vmcnt(1)
	v_pk_fma_f32 v[8:9], v[12:13], v[24:25], v[8:9]
	v_pk_add_f32 v[12:13], v[22:23], 1.0 op_sel_hi:[1,0]
	s_nop 0
	v_div_scale_f32 v22, s[10:11], v13, v13, 1.0
	v_rcp_f32_e32 v23, v22
	s_nop 0
	v_fma_f32 v24, -v22, v23, 1.0
	v_fmac_f32_e32 v23, v24, v23
	v_div_scale_f32 v24, vcc, 1.0, v13, 1.0
	v_mul_f32_e32 v25, v24, v23
	v_fma_f32 v26, -v22, v25, v24
	v_fmac_f32_e32 v25, v26, v23
	v_fma_f32 v22, -v22, v25, v24
	v_div_fmas_f32 v22, v22, v23, v25
	v_div_fixup_f32 v13, v22, v13, 1.0
	v_div_scale_f32 v22, s[10:11], v12, v12, 1.0
	v_rcp_f32_e32 v23, v22
	s_nop 0
	v_fma_f32 v24, -v22, v23, 1.0
	v_fmac_f32_e32 v23, v24, v23
	v_div_scale_f32 v24, vcc, 1.0, v12, 1.0
	v_mul_f32_e32 v25, v24, v23
	v_fma_f32 v26, -v22, v25, v24
	v_fmac_f32_e32 v25, v26, v23
	v_fma_f32 v22, -v22, v25, v24
	v_div_fmas_f32 v22, v22, v23, v25
	v_div_fixup_f32 v12, v22, v12, 1.0
	v_pk_fma_f32 v[10:11], v[14:15], v[12:13], v[10:11]
	global_store_dwordx4 v[18:19], v[8:11], off
	s_nop 1
	v_pk_add_f32 v[8:9], v[20:21], 1.0 op_sel_hi:[1,0]
	s_nop 0
	v_div_scale_f32 v10, s[10:11], v9, v9, 1.0
	v_rcp_f32_e32 v11, v10
	s_nop 0
	v_fma_f32 v12, -v10, v11, 1.0
	v_fmac_f32_e32 v11, v12, v11
	v_div_scale_f32 v12, vcc, 1.0, v9, 1.0
	v_mul_f32_e32 v13, v12, v11
	v_fma_f32 v14, -v10, v13, v12
	v_fmac_f32_e32 v13, v14, v11
	v_fma_f32 v10, -v10, v13, v12
	v_div_fmas_f32 v10, v10, v11, v13
	v_div_fixup_f32 v9, v10, v9, 1.0
	v_div_scale_f32 v10, s[10:11], v8, v8, 1.0
	v_rcp_f32_e32 v11, v10
	s_nop 0
	v_fma_f32 v12, -v10, v11, 1.0
	v_fmac_f32_e32 v11, v12, v11
	v_div_scale_f32 v12, vcc, 1.0, v8, 1.0
	v_mul_f32_e32 v13, v12, v11
	v_fma_f32 v14, -v10, v13, v12
	v_fmac_f32_e32 v13, v14, v11
	v_fma_f32 v10, -v10, v13, v12
	v_div_fmas_f32 v10, v10, v11, v13
	v_div_fixup_f32 v8, v10, v8, 1.0
	s_waitcnt vmcnt(1)
	v_pk_fma_f32 v[0:1], v[4:5], v[8:9], v[0:1]
	v_pk_add_f32 v[4:5], v[16:17], 1.0 op_sel_hi:[1,0]
	s_nop 0
	v_div_scale_f32 v8, s[10:11], v5, v5, 1.0
	v_rcp_f32_e32 v9, v8
	s_nop 0
	v_fma_f32 v10, -v8, v9, 1.0
	v_fmac_f32_e32 v9, v10, v9
	v_div_scale_f32 v10, vcc, 1.0, v5, 1.0
	v_mul_f32_e32 v11, v10, v9
	v_fma_f32 v12, -v8, v11, v10
	v_fmac_f32_e32 v11, v12, v9
	v_fma_f32 v8, -v8, v11, v10
	v_div_fmas_f32 v8, v8, v9, v11
	v_div_fixup_f32 v5, v8, v5, 1.0
	v_div_scale_f32 v8, s[10:11], v4, v4, 1.0
	v_rcp_f32_e32 v9, v8
	s_nop 0
	v_fma_f32 v10, -v8, v9, 1.0
	v_fmac_f32_e32 v9, v10, v9
	v_div_scale_f32 v10, vcc, 1.0, v4, 1.0
	v_mul_f32_e32 v11, v10, v9
	v_fma_f32 v12, -v8, v11, v10
	v_fmac_f32_e32 v11, v12, v9
	v_fma_f32 v8, -v8, v11, v10
	v_div_fmas_f32 v8, v8, v9, v11
	v_div_fixup_f32 v4, v8, v4, 1.0
	v_pk_fma_f32 v[2:3], v[6:7], v[4:5], v[2:3]
	global_store_dwordx4 v[18:19], v[0:3], off offset:16
	s_andn2_b64 vcc, exec, s[0:1]
	s_cbranch_vccz .LBB0_514

; template <int BN, bool SWAP> ...
;     ...
;   const bfu* Apn = chain ? (An + (size_t)lrow * ldan + lch) : Ap;
;   const bfu* Bpn = chain ? (Bn + (size_t)lrow * ldbn + lch) : Bp;
;   auto gl = [&](bf16x8 (&ra)[4], bf16x8 (&rb)[NJ], int kt) {
;     const bool nx = (kt >= nk);
;     const bfu* pa = nx ? (chain ? Apn + (kt - nk) * 64 : Ap + (nk - 1) * 64) : Ap + kt * 64;
;     const bfu* pb = nx ? (chain ? Bpn + (kt - nk) * 64 : Bp + (nk - 1) * 64) : Bp + kt * 64;
;     const size_t sa = (nx && chain) ? (size_t)ldan : (size_t)lda, sb = (nx && chain) ? (size_t)ldbn : (size_t)ldb;
; #pragma unroll
;     for (int q = 0; q < 4; ++q) ra[q] = gld16(pa + (size_t)(32 * q) * sa);
; #pragma unroll
;     for (int q = 0; q < NJ; ++q) rb[q] = gld16(pb + (size_t)(32 * q) * sb);
;   };
;   auto wt = [&](bf16x8 (&ra)[4], bf16x8 (&rb)[NJ]) {
;     if (NJ == 4) asm volatile("s_waitcnt vmcnt(8)" : "+v"(ra[0]), "+v"(ra[1]), "+v"(ra[2]), "+v"(ra[3]), "+v"(rb[0]), "+v"(rb[1]), "+v"(rb[NJ - 2]), "+v"(rb[NJ - 1]) : : "memory");
;     else asm volatile("s_waitcnt vmcnt(6)" : "+v"(ra[0]), "+v"(ra[1]), "+v"(ra[2]), "+v"(ra[3]), "+v"(rb[0]), "+v"(rb[1]) : : "memory");
;   };
;   auto st = [&](const bf16x8 (&ra)[4], const bf16x8 (&rb)[NJ], int buf) {
; #pragma unroll
;     for (int q = 0; q < 4; ++q) *(bf16x8*)(As + (buf * 128 + lrow + 32 * q) * 72 + lch) = ra[q];
; #pragma unroll
;     for (int q = 0; q < NJ; ++q) *(bf16x8*)(Bs + (buf * BN + brow + ((SWAP && NJ == 4) ? (8 * (q & 1) + 64 * (q >> 1)) : 32 * q)) * 72 + lch) = rb[q];
;   };
; template <int G>
; __device__ __forceinline__ void p6(const Params& P, const Ptrs<G>& w, int pass, int layer, bfu* sm, const XcdInfo& xi) {
;     ...
;   for (int tile = tstart; tile < tend; tile += tstep) {
;     int nt, mt;
;     if (xi.ok) xcd_tile(tile, xi.x, MT / 8, 16, mt, nt); else { nt = tile / MT; mt = tile % MT; }
;     const int n0 = nt * 64, m0 = mt * 128;
;     f32x4 Ga[4][2], Pa[4][2];
; #pragma unroll
;     for (int i = 0; i < 4; ++i)
; #pragma unroll
;       for (int j = 0; j < 2; ++j) { Ga[i][j] = (f32x4){0.f, 0.f, 0.f, 0.f}; Pa[i][j] = (f32x4){0.f, 0.f, 0.f, 0.f}; }
;     const bfu* Ap6 = pbl + (size_t)m0 * 256;
;     const bfu* Bp6 = Wl + L::W_IN + L::W_B + L::W_O + L::W_G + (size_t)n0 * 256;
;     gemm_core<64, true>(w.rb() + (size_t)m0 * 1024, 1024, Wl + L::W_IN + L::W_B + L::W_O + (size_t)n0 * 1024, 1024, 1024, Ga, sm, Ap6, 256, Bp6, 256);
.LBB0_507:
	s_lshl_b32 s14, s12, 6
	s_lshl_b32 s12, s2, 7
	s_ashr_i32 s13, s12, 31
	s_lshl_b64 s[0:1], s[12:13], 9
	s_add_u32 s16, s24, s0
	s_addc_u32 s17, s25, s1
	s_ashr_i32 s15, s14, 31
	s_lshl_b64 s[0:1], s[14:15], 9
	s_add_u32 s18, s28, s0
	s_addc_u32 s19, s29, s1
	s_lshl_b64 s[0:1], s[12:13], 11
	v_readlane_b32 s20, v252, 38
	v_readlane_b32 s21, v252, 39
	s_add_u32 s0, s20, s0
	v_mov_b32_e32 v58, v174
	s_addc_u32 s1, s21, s1
	s_lshl_b64 s[20:21], s[14:15], 11
	s_add_u32 s20, s26, s20
	v_ashrrev_i32_e32 v56, 3, v58
	v_ashrrev_i32_e32 v57, 31, v56
	s_addc_u32 s21, s27, s21
	v_lshlrev_b64 v[0:1], 11, v[56:57]
	v_lshlrev_b32_e32 v4, 4, v58
	v_lshl_add_u64 v[2:3], s[0:1], 0, v[0:1]
	v_and_b32_e32 v152, 0x70, v4
	v_lshl_add_u64 v[0:1], s[20:21], 0, v[0:1]
	v_lshl_add_u64 v[42:43], v[0:1], 0, v[152:153]
	v_lshlrev_b32_e32 v0, 2, v56
	v_lshrrev_b32_e32 v1, 1, v56
	v_lshl_add_u64 v[40:41], v[2:3], 0, v[152:153]
	v_and_b32_e32 v0, 16, v0
	v_and_b32_e32 v1, 12, v1
	v_and_b32_e32 v2, 3, v56
	v_or3_b32 v59, v2, v1, v0
	v_lshlrev_b64 v[0:1], 9, v[56:57]
	v_lshl_add_u64 v[2:3], s[16:17], 0, v[0:1]
	v_lshl_add_u64 v[0:1], s[18:19], 0, v[0:1]
	v_lshl_add_u64 v[52:53], v[2:3], 0, v[152:153]
	v_lshl_add_u64 v[54:55], v[0:1], 0, v[152:153]
	global_load_dwordx4 v[0:3], v[40:41], off
	v_lshl_add_u64 v[4:5], v[40:41], 0, s[76:77]
	global_load_dwordx4 v[8:11], v[4:5], off
	v_lshl_add_u64 v[4:5], v[40:41], 0, s[8:9]
	global_load_dwordx4 v[28:31], v[4:5], off
	v_lshl_add_u64 v[4:5], v[40:41], 0, s[78:79]
	global_load_dwordx4 v[32:35], v[4:5], off
	global_load_dwordx4 v[44:47], v[42:43], off
	v_lshl_add_u64 v[4:5], v[42:43], 0, s[76:77]
	global_load_dwordx4 v[48:51], v[4:5], off
	v_lshl_add_u64 v[4:5], v[40:41], 0, s[80:81]
	s_mov_b64 s[0:1], 0x10080
	global_load_dwordx4 v[4:7], v[4:5], off
	v_lshl_add_u64 v[12:13], v[40:41], 0, s[0:1]
	global_load_dwordx4 v[12:15], v[12:13], off
	v_lshl_add_u64 v[16:17], v[40:41], 0, s[82:83]
	global_load_dwordx4 v[16:19], v[16:17], off
	v_lshl_add_u64 v[20:21], v[40:41], 0, s[84:85]
	v_lshl_add_u64 v[24:25], v[42:43], 0, s[80:81]
	global_load_dwordx4 v[20:23], v[20:21], off
	global_load_dwordx4 v[24:27], v[24:25], off
	v_lshl_add_u64 v[36:37], v[42:43], 0, s[0:1]
	global_load_dwordx4 v[36:39], v[36:37], off
	s_barrier
	s_waitcnt vmcnt(6)
	v_add_u32_e32 v100, 4, v56
	v_and_b32_e32 v100, 8, v100
	v_lshlrev_b32_e32 v100, 1, v100
	v_xor_b32_e32 v100, v152, v100
	v_mad_u32_u24 v56, v56, s89, v100
	v_and_b32_e32 v60, 15, v58
	ds_write_b128 v56, v[0:3]
	ds_write_b128 v56, v[8:11] offset:4608
	ds_write_b128 v56, v[28:31] offset:9216
	ds_write_b128 v56, v[32:35] offset:13824
	v_lshrrev_b32_e32 v1, 1, v58
	v_and_or_b32 v2, v1, s74, v60
	v_and_b32_e32 v0, 48, v58
	v_add_u32_e32 v100, 4, v59
	v_and_b32_e32 v100, 8, v100
	v_lshlrev_b32_e32 v100, 1, v100
	v_xor_b32_e32 v100, v152, v100
	v_mad_u32_u24 v57, v59, s89, v100
	v_add_u32_e32 v100, 4, v58
	v_and_b32_e32 v100, 8, v100
	v_lshlrev_b32_e32 v100, 1, v100
	v_xor_b32_e32 v0, v0, v100
	v_mad_u32_u24 v58, v2, s89, v0
	v_and_or_b32 v1, v1, 32, v60
	v_mul_u32_u24_e32 v1, 0x48, v1
	v_lshl_add_u32 v59, v1, 1, v0
	v_mov_b32_e32 v0, 0
	ds_write_b128 v57, v[44:47] offset:36864
	ds_write_b128 v57, v[48:51] offset:41472
	s_mov_b32 s13, 0
	s_mov_b32 s0, 0
	v_mov_b32_e32 v1, v0
	v_mov_b32_e32 v2, v0
	v_mov_b32_e32 v3, v0
	v_mov_b32_e32 v8, v0
	v_mov_b32_e32 v9, v0
	v_mov_b32_e32 v10, v0
	v_mov_b32_e32 v11, v0
	v_mov_b32_e32 v28, v0
	v_mov_b32_e32 v29, v0
	v_mov_b32_e32 v30, v0
	v_mov_b32_e32 v31, v0
	v_mov_b32_e32 v32, v0
	v_mov_b32_e32 v33, v0
	v_mov_b32_e32 v34, v0
	v_mov_b32_e32 v35, v0
	v_mov_b32_e32 v44, v0
	v_mov_b32_e32 v45, v0
	v_mov_b32_e32 v46, v0
	v_mov_b32_e32 v47, v0
	v_mov_b32_e32 v48, v0
	v_mov_b32_e32 v49, v0
	v_mov_b32_e32 v50, v0
	v_mov_b32_e32 v51, v0
	v_mov_b32_e32 v60, v0
	v_mov_b32_e32 v61, v0
	v_mov_b32_e32 v62, v0
	v_mov_b32_e32 v63, v0
	v_mov_b32_e32 v64, v0
	v_mov_b32_e32 v65, v0
	v_mov_b32_e32 v66, v0
	v_mov_b32_e32 v67, v0
	s_waitcnt lgkmcnt(0)
	s_barrier
